# epilogue row reductions: the xor-32 shuffle step done with v_permlane32_swap on the VALU instead of ds_bpermute (ff1 and gate-tile epilogues)
# baseline (speedup 1.0000x reference)
; __device__ __forceinline__ unsigned pk2(float lo, float hi) { f32x2 v = {lo, hi}; bf16x2_t b = __builtin_convertvector(v, bf16x2_t); return __builtin_bit_cast(unsigned, b); }
; __device__ __forceinline__ void row_rinv8(float (&rs)[8], const float* ssq, int row0, int fq) {
;     f32x4 pv[8];
; #pragma unroll
;     for (int i = 0; i < 8; ++i) pv[i] = *(const f32x4*)(ssq + (size_t)(row0 + (i >> 2) * HALF + (i & 3) * 16) * 16 + 4 * fq);
; #pragma unroll
;     for (int i = 0; i < 8; ++i) { float s = (pv[i][0] + pv[i][1]) + (pv[i][2] + pv[i][3]); s += __shfl_xor(s, 16); s += __shfl_xor(s, 32); rs[i] = __builtin_amdgcn_rsqf(s * (1.0f / DM) + EPS); }
; }
;     __device__ __forceinline__ void operator()(const Acc& acc, const Unit& u, int wr, int wc, int fr, int fq) const {
;         int ldc = this->ldc; asm volatile("" : "+s"(ldc));
;         const int row0 = u.pm * BM + wr * 64 + fr, col0 = u.pn * BM + wc * 32 + 8 * fq;
;         float rsv[8];
;         if (ssq) row_rinv8(rsv, ssq, row0, fq); else {
; #pragma unroll
;             for (int i = 0; i < 8; ++i) rsv[i] = 1.0f; }
; #pragma unroll
;         for (int ai = 0; ai < 2; ++ai)
; #pragma unroll
;             for (int m = 0; m < 4; ++m) { bf16_t* rowp = O + (size_t)(row0 + ai * HALF + m * 16) * ldc + col0;
;                 const float rs = rsv[ai * 4 + m];
; #pragma unroll
;                 for (int bj = 0; bj < 2; ++bj) { f32x4 v0 = acc[ai][bj][m][0] * rs, v1 = acc[ai][bj][m][1] * rs;
;                     if (ACT == 1) {
; #pragma unroll
;                         for (int i = 0; i < 4; ++i) { float a = fmaxf(v0[i], 0.f), b = fmaxf(v1[i], 0.f); v0[i] = a * a; v1[i] = b * b; } }
;                     u32x4 w; w.x = pk2(v0[0], v0[1]); w.y = pk2(v0[2], v0[3]); w.z = pk2(v1[0], v1[1]); w.w = pk2(v1[2], v1[3]);
;                     *(u32x4*)(rowp + bj * HALF) = w; } asm volatile("" ::: "memory"); }
.LBB0_212:
	v_mov_b32_e32 v130, v171
	v_mov_b32_e32 v180, v173
	s_lshl_b32 s1, s82, 8
	s_add_i32 s1, s1, s65
	v_add_u32_e32 v174, s1, v130
	v_lshlrev_b32_e32 v130, 2, v180
	v_ashrrev_i32_e32 v131, 31, v130
	v_ashrrev_i32_e32 v175, 31, v174
	v_lshl_add_u64 v[130:131], v[130:131], 2, s[24:25]
	v_lshlrev_b64 v[132:133], 6, v[174:175]
	s_movk_i32 s0, 0x1000
	v_lshl_add_u64 v[132:133], v[130:131], 0, v[132:133]
	global_load_dwordx4 v[182:185], v[132:133], off
	v_add_u32_e32 v168, 16, v174
	v_ashrrev_i32_e32 v169, 31, v168
	v_lshlrev_b64 v[132:133], 6, v[168:169]
	v_lshl_add_u64 v[132:133], v[130:131], 0, v[132:133]
	global_load_dwordx4 v[196:199], v[132:133], off
	v_add_u32_e32 v166, 32, v174
	v_ashrrev_i32_e32 v167, 31, v166
	v_lshlrev_b64 v[132:133], 6, v[166:167]
	v_lshl_add_u64 v[132:133], v[130:131], 0, v[132:133]
	global_load_dwordx4 v[200:203], v[132:133], off
	v_add_u32_e32 v164, 48, v174
	v_ashrrev_i32_e32 v165, 31, v164
	v_lshlrev_b64 v[132:133], 6, v[164:165]
	v_add_u32_e32 v162, 0x80, v174
	v_lshl_add_u64 v[132:133], v[130:131], 0, v[132:133]
	v_ashrrev_i32_e32 v163, 31, v162
	global_load_dwordx4 v[204:207], v[132:133], off
	v_lshlrev_b64 v[132:133], 6, v[162:163]
	v_add_u32_e32 v160, 0x90, v174
	v_lshl_add_u64 v[132:133], v[130:131], 0, v[132:133]
	v_ashrrev_i32_e32 v161, 31, v160
	global_load_dwordx4 v[142:145], v[132:133], off
	v_lshlrev_b64 v[132:133], 6, v[160:161]
	v_add_u32_e32 v158, 0xa0, v174
	v_lshl_add_u64 v[132:133], v[130:131], 0, v[132:133]
	v_ashrrev_i32_e32 v159, 31, v158
	global_load_dwordx4 v[138:141], v[132:133], off
	v_lshlrev_b64 v[132:133], 6, v[158:159]
	v_add_u32_e32 v156, 0xb0, v174
	v_lshl_add_u64 v[132:133], v[130:131], 0, v[132:133]
	v_ashrrev_i32_e32 v157, 31, v156
	global_load_dwordx4 v[134:137], v[132:133], off
	v_lshlrev_b64 v[132:133], 6, v[156:157]
	v_lshl_add_u64 v[130:131], v[130:131], 0, v[132:133]
	global_load_dwordx4 v[130:133], v[130:131], off
	v_and_b32_e32 v159, 64, v224
	v_xor_b32_e32 v157, 16, v224
	v_add_u32_e32 v159, 64, v159
	v_cmp_lt_i32_e32 vcc, v157, v159
	v_xor_b32_e32 v161, 32, v224
	s_lshl_b32 s1, s83, 8
	v_cndmask_b32_e32 v157, v224, v157, vcc
	v_cmp_lt_i32_e32 vcc, v161, v159
	v_lshlrev_b32_e32 v157, 2, v157
	s_or_b32 s1, s1, s67
	v_cndmask_b32_e32 v159, v224, v161, vcc
	v_lshlrev_b32_e32 v159, 2, v159
	s_andn2_b64 vcc, exec, s[38:39]
	s_waitcnt vmcnt(0) lgkmcnt(0)
	v_mov_b32_e32 v208, v183
	v_mov_b32_e32 v209, v184
	v_mov_b32_e32 v183, v185
	v_pk_add_f32 v[182:183], v[208:209], v[182:183]
	s_nop 0
	v_add_f32_e32 v161, v182, v183
	ds_bpermute_b32 v163, v157, v161
	v_mov_b32_e32 v182, v197
	v_mov_b32_e32 v183, v198
	v_mov_b32_e32 v197, v199
	v_pk_add_f32 v[182:183], v[182:183], v[196:197]
	s_waitcnt lgkmcnt(0)
	v_add_f32_e32 v161, v161, v163
	v_mov_b32_e32 v163, v161
	s_nop 1
	v_permlane32_swap_b32_e32 v163, v161
	s_waitcnt lgkmcnt(0)
	v_add_f32_e32 v161, v161, v163
	v_fmamk_f32 v161, v161, 0x3a800000, v225
	v_rsq_f32_e32 v178, v161
	v_add_f32_e32 v161, v182, v183
	ds_bpermute_b32 v163, v157, v161
	v_mov_b32_e32 v182, v201
	v_mov_b32_e32 v183, v202
	v_mov_b32_e32 v201, v203
	v_pk_add_f32 v[182:183], v[182:183], v[200:201]
	s_waitcnt lgkmcnt(0)
	v_add_f32_e32 v161, v161, v163
	v_mov_b32_e32 v163, v161
	s_nop 1
	v_permlane32_swap_b32_e32 v163, v161
	v_pk_mul_f32 v[122:123], v[122:123], v[178:179] op_sel_hi:[1,0]
	v_pk_mul_f32 v[128:129], v[128:129], v[178:179] op_sel_hi:[1,0]
	v_pk_mul_f32 v[126:127], v[126:127], v[178:179] op_sel_hi:[1,0]
	v_pk_mul_f32 v[124:125], v[124:125], v[178:179] op_sel_hi:[1,0]
	s_waitcnt lgkmcnt(0)
	v_add_f32_e32 v161, v161, v163
	v_fmamk_f32 v161, v161, 0x3a800000, v225
	v_rsq_f32_e32 v176, v161
	v_add_f32_e32 v161, v182, v183
	ds_bpermute_b32 v163, v157, v161
	v_mov_b32_e32 v182, v205
	v_mov_b32_e32 v183, v206
	v_mov_b32_e32 v205, v207
	v_pk_add_f32 v[182:183], v[182:183], v[204:205]
	s_waitcnt lgkmcnt(0)
	v_add_f32_e32 v161, v161, v163
	v_mov_b32_e32 v163, v161
	s_nop 1
	v_permlane32_swap_b32_e32 v163, v161
	v_max_f32_e32 v122, 0, v122
	v_max_f32_e32 v123, 0, v123
	v_max_f32_e32 v126, 0, v126
	v_max_f32_e32 v127, 0, v127
	s_waitcnt lgkmcnt(0)
	v_add_f32_e32 v161, v161, v163
	v_fmamk_f32 v161, v161, 0x3a800000, v225
	v_rsq_f32_e32 v172, v161
	v_add_f32_e32 v161, v182, v183
	ds_bpermute_b32 v163, v157, v161
	v_mov_b32_e32 v182, v143
	v_mov_b32_e32 v183, v144
	v_mov_b32_e32 v143, v145
	v_mov_b32_e32 v144, v139
	v_mov_b32_e32 v145, v140
	v_mov_b32_e32 v139, v141
	v_mov_b32_e32 v140, v135
	v_mov_b32_e32 v141, v136
	v_mov_b32_e32 v135, v137
	v_mov_b32_e32 v136, v131
	v_mov_b32_e32 v137, v132
	v_mov_b32_e32 v131, v133
	v_lshl_add_u32 v132, v180, 3, s1
	v_pk_add_f32 v[134:135], v[140:141], v[134:135]
	v_pk_add_f32 v[130:131], v[136:137], v[130:131]
	v_ashrrev_i32_e32 v133, 31, v132
	v_mad_i64_i32 v[136:137], s[20:21], v174, s0, 0
	v_pk_mul_f32 v[140:141], v[122:123], v[122:123]
	v_max_f32_e32 v122, 0, v128
	v_max_f32_e32 v124, 0, v124
	v_max_f32_e32 v123, 0, v129
	v_max_f32_e32 v125, 0, v125
	v_pk_add_f32 v[138:139], v[144:145], v[138:139]
	v_lshl_add_u64 v[136:137], v[136:137], 1, s[56:57]
	v_lshlrev_b64 v[132:133], 1, v[132:133]
	v_pk_mul_f32 v[126:127], v[126:127], v[126:127]
	v_pk_mul_f32 v[128:129], v[122:123], v[122:123]
	v_pk_mul_f32 v[144:145], v[124:125], v[124:125]
	v_pk_mul_f32 v[114:115], v[114:115], v[178:179] op_sel_hi:[1,0]
	v_lshl_add_u64 v[136:137], v[136:137], 0, v[132:133]
	v_cvt_pk_bf16_f32 v122, v126, v127
	v_cvt_pk_bf16_f32 v123, v128, v129
	v_cvt_pk_bf16_f32 v124, v140, v141
	v_cvt_pk_bf16_f32 v125, v144, v145
	v_pk_mul_f32 v[120:121], v[120:121], v[178:179] op_sel_hi:[1,0]
	v_pk_mul_f32 v[118:119], v[118:119], v[178:179] op_sel_hi:[1,0]
	v_pk_mul_f32 v[116:117], v[116:117], v[178:179] op_sel_hi:[1,0]
	v_max_f32_e32 v114, 0, v114
	v_max_f32_e32 v115, 0, v115
	v_pk_add_f32 v[142:143], v[182:183], v[142:143]
	global_store_dwordx4 v[136:137], v[122:125], off
	v_max_f32_e32 v118, 0, v118
	v_max_f32_e32 v119, 0, v119
	v_pk_mul_f32 v[122:123], v[114:115], v[114:115]
	v_max_f32_e32 v114, 0, v120
	v_max_f32_e32 v116, 0, v116
	v_max_f32_e32 v115, 0, v121
	v_max_f32_e32 v117, 0, v117
	s_waitcnt lgkmcnt(0)
; __device__ __forceinline__ unsigned pk2(float lo, float hi) { f32x2 v = {lo, hi}; bf16x2_t b = __builtin_convertvector(v, bf16x2_t); return __builtin_bit_cast(unsigned, b); }
; __device__ __forceinline__ void row_rinv8(float (&rs)[8], const float* ssq, int row0, int fq) {
;     ...
;     for (int i = 0; i < 8; ++i) { float s = (pv[i][0] + pv[i][1]) + (pv[i][2] + pv[i][3]); s += __shfl_xor(s, 16); s += __shfl_xor(s, 32); rs[i] = __builtin_amdgcn_rsqf(s * (1.0f / DM) + EPS); }
;     __device__ __forceinline__ void operator()(const Acc& acc, const Unit& u, int wr, int wc, int fr, int fq) const {
;     ...
; #pragma unroll
;         for (int ai = 0; ai < 2; ++ai)
; #pragma unroll
;             for (int m = 0; m < 4; ++m) { bf16_t* rowp = O + (size_t)(row0 + ai * HALF + m * 16) * ldc + col0;
;                 const float rs = rsv[ai * 4 + m];
; #pragma unroll
;                 for (int bj = 0; bj < 2; ++bj) { f32x4 v0 = acc[ai][bj][m][0] * rs, v1 = acc[ai][bj][m][1] * rs;
;                     if (ACT == 1) {
; #pragma unroll
;                         for (int i = 0; i < 4; ++i) { float a = fmaxf(v0[i], 0.f), b = fmaxf(v1[i], 0.f); v0[i] = a * a; v1[i] = b * b; } }
;                     u32x4 w; w.x = pk2(v0[0], v0[1]); w.y = pk2(v0[2], v0[3]); w.z = pk2(v1[0], v1[1]); w.w = pk2(v1[2], v1[3]);
;                     *(u32x4*)(rowp + bj * HALF) = w; } asm volatile("" ::: "memory"); }
	v_add_f32_e32 v161, v161, v163
	v_add_f32_e32 v142, v142, v143
	v_pk_mul_f32 v[118:119], v[118:119], v[118:119]
	v_pk_mul_f32 v[120:121], v[114:115], v[114:115]
	v_pk_mul_f32 v[124:125], v[116:117], v[116:117]
	v_pk_mul_f32 v[106:107], v[106:107], v[176:177] op_sel_hi:[1,0]
	v_mov_b32_e32 v163, v161
	s_nop 1
	v_permlane32_swap_b32_e32 v163, v161
	ds_bpermute_b32 v143, v157, v142
	v_cvt_pk_bf16_f32 v114, v118, v119
	v_cvt_pk_bf16_f32 v115, v120, v121
	v_cvt_pk_bf16_f32 v116, v122, v123
	v_cvt_pk_bf16_f32 v117, v124, v125
	v_pk_mul_f32 v[112:113], v[112:113], v[176:177] op_sel_hi:[1,0]
	v_pk_mul_f32 v[110:111], v[110:111], v[176:177] op_sel_hi:[1,0]
	v_pk_mul_f32 v[108:109], v[108:109], v[176:177] op_sel_hi:[1,0]
	v_max_f32_e32 v106, 0, v106
	v_max_f32_e32 v107, 0, v107
	global_store_dwordx4 v[136:137], v[114:117], off offset:256
	v_max_f32_e32 v110, 0, v110
	v_max_f32_e32 v111, 0, v111
	v_mad_i64_i32 v[114:115], s[20:21], v168, s0, 0
	v_pk_mul_f32 v[116:117], v[106:107], v[106:107]
	v_max_f32_e32 v106, 0, v112
	v_max_f32_e32 v108, 0, v108
	v_max_f32_e32 v107, 0, v113
	v_max_f32_e32 v109, 0, v109
	v_lshl_add_u64 v[114:115], v[114:115], 1, s[56:57]
	v_pk_mul_f32 v[110:111], v[110:111], v[110:111]
	v_pk_mul_f32 v[112:113], v[106:107], v[106:107]
	v_pk_mul_f32 v[118:119], v[108:109], v[108:109]
	v_pk_mul_f32 v[98:99], v[98:99], v[176:177] op_sel_hi:[1,0]
	v_lshl_add_u64 v[114:115], v[114:115], 0, v[132:133]
	v_cvt_pk_bf16_f32 v106, v110, v111
	v_cvt_pk_bf16_f32 v107, v112, v113
	v_cvt_pk_bf16_f32 v108, v116, v117
	v_cvt_pk_bf16_f32 v109, v118, v119
	v_pk_mul_f32 v[104:105], v[104:105], v[176:177] op_sel_hi:[1,0]
	v_pk_mul_f32 v[102:103], v[102:103], v[176:177] op_sel_hi:[1,0]
	v_pk_mul_f32 v[100:101], v[100:101], v[176:177] op_sel_hi:[1,0]
	v_max_f32_e32 v98, 0, v98
	v_max_f32_e32 v99, 0, v99
	global_store_dwordx4 v[114:115], v[106:109], off
	v_max_f32_e32 v102, 0, v102
	v_max_f32_e32 v103, 0, v103
	v_pk_mul_f32 v[106:107], v[98:99], v[98:99]
	v_max_f32_e32 v98, 0, v104
	v_max_f32_e32 v100, 0, v100
	v_max_f32_e32 v99, 0, v105
	v_max_f32_e32 v101, 0, v101
	s_waitcnt lgkmcnt(0)
	v_add_f32_e32 v161, v161, v163
	v_add_f32_e32 v142, v142, v143
	v_add_f32_e32 v138, v138, v139
	v_pk_mul_f32 v[102:103], v[102:103], v[102:103]
	v_pk_mul_f32 v[104:105], v[98:99], v[98:99]
	v_pk_mul_f32 v[108:109], v[100:101], v[100:101]
	v_pk_mul_f32 v[90:91], v[90:91], v[172:173] op_sel_hi:[1,0]
	v_fmamk_f32 v161, v161, 0x3a800000, v225
	v_mov_b32_e32 v143, v142
	s_nop 1
	v_permlane32_swap_b32_e32 v143, v142
	ds_bpermute_b32 v139, v157, v138
	v_cvt_pk_bf16_f32 v98, v102, v103
	v_cvt_pk_bf16_f32 v99, v104, v105
	v_cvt_pk_bf16_f32 v100, v106, v107
	v_cvt_pk_bf16_f32 v101, v108, v109
	v_pk_mul_f32 v[96:97], v[96:97], v[172:173] op_sel_hi:[1,0]
	v_pk_mul_f32 v[94:95], v[94:95], v[172:173] op_sel_hi:[1,0]
	v_pk_mul_f32 v[92:93], v[92:93], v[172:173] op_sel_hi:[1,0]
	v_max_f32_e32 v90, 0, v90
	v_max_f32_e32 v91, 0, v91
	v_rsq_f32_e32 v170, v161
	global_store_dwordx4 v[114:115], v[98:101], off offset:256
	v_max_f32_e32 v94, 0, v94
	v_max_f32_e32 v95, 0, v95
	v_mad_i64_i32 v[98:99], s[20:21], v166, s0, 0
	v_pk_mul_f32 v[100:101], v[90:91], v[90:91]
	v_max_f32_e32 v90, 0, v96
	v_max_f32_e32 v92, 0, v92
	v_max_f32_e32 v91, 0, v97
	v_max_f32_e32 v93, 0, v93
	v_lshl_add_u64 v[98:99], v[98:99], 1, s[56:57]
	v_pk_mul_f32 v[94:95], v[94:95], v[94:95]
	v_pk_mul_f32 v[96:97], v[90:91], v[90:91]
	v_pk_mul_f32 v[102:103], v[92:93], v[92:93]
	v_pk_mul_f32 v[82:83], v[82:83], v[172:173] op_sel_hi:[1,0]
	v_lshl_add_u64 v[98:99], v[98:99], 0, v[132:133]
	v_cvt_pk_bf16_f32 v90, v94, v95
	v_cvt_pk_bf16_f32 v91, v96, v97
	v_cvt_pk_bf16_f32 v92, v100, v101
	v_cvt_pk_bf16_f32 v93, v102, v103
	v_pk_mul_f32 v[88:89], v[88:89], v[172:173] op_sel_hi:[1,0]
	v_pk_mul_f32 v[86:87], v[86:87], v[172:173] op_sel_hi:[1,0]
	v_pk_mul_f32 v[84:85], v[84:85], v[172:173] op_sel_hi:[1,0]
	v_max_f32_e32 v82, 0, v82
	v_max_f32_e32 v83, 0, v83
	global_store_dwordx4 v[98:99], v[90:93], off
	v_max_f32_e32 v86, 0, v86
	v_max_f32_e32 v87, 0, v87
	v_pk_mul_f32 v[90:91], v[82:83], v[82:83]
	v_max_f32_e32 v82, 0, v88
	v_max_f32_e32 v84, 0, v84
	v_max_f32_e32 v83, 0, v89
	v_max_f32_e32 v85, 0, v85
	s_waitcnt lgkmcnt(0)
	v_add_f32_e32 v142, v142, v143
	v_add_f32_e32 v138, v138, v139
	v_add_f32_e32 v134, v134, v135
	v_pk_mul_f32 v[86:87], v[86:87], v[86:87]
	v_pk_mul_f32 v[88:89], v[82:83], v[82:83]
	v_pk_mul_f32 v[92:93], v[84:85], v[84:85]
	v_pk_mul_f32 v[74:75], v[74:75], v[170:171] op_sel_hi:[1,0]
	v_fmamk_f32 v142, v142, 0x3a800000, v225
	v_mov_b32_e32 v139, v138
	s_nop 1
	v_permlane32_swap_b32_e32 v139, v138
	ds_bpermute_b32 v135, v157, v134
	v_cvt_pk_bf16_f32 v82, v86, v87
	v_cvt_pk_bf16_f32 v83, v88, v89
	v_cvt_pk_bf16_f32 v84, v90, v91
	v_cvt_pk_bf16_f32 v85, v92, v93
	v_pk_mul_f32 v[80:81], v[80:81], v[170:171] op_sel_hi:[1,0]
	v_pk_mul_f32 v[78:79], v[78:79], v[170:171] op_sel_hi:[1,0]
	v_pk_mul_f32 v[76:77], v[76:77], v[170:171] op_sel_hi:[1,0]
	v_max_f32_e32 v74, 0, v74
	v_max_f32_e32 v75, 0, v75
	v_rsq_f32_e32 v142, v142
	global_store_dwordx4 v[98:99], v[82:85], off offset:256
	v_max_f32_e32 v78, 0, v78
	v_max_f32_e32 v79, 0, v79
	v_mad_i64_i32 v[82:83], s[20:21], v164, s0, 0
	v_pk_mul_f32 v[84:85], v[74:75], v[74:75]
	v_max_f32_e32 v74, 0, v80
	v_max_f32_e32 v76, 0, v76
	v_max_f32_e32 v75, 0, v81
	v_max_f32_e32 v77, 0, v77
	v_lshl_add_u64 v[82:83], v[82:83], 1, s[56:57]
	v_pk_mul_f32 v[78:79], v[78:79], v[78:79]
	v_pk_mul_f32 v[80:81], v[74:75], v[74:75]
	v_pk_mul_f32 v[86:87], v[76:77], v[76:77]
	v_pk_mul_f32 v[66:67], v[66:67], v[170:171] op_sel_hi:[1,0]
	v_lshl_add_u64 v[82:83], v[82:83], 0, v[132:133]
	v_cvt_pk_bf16_f32 v74, v78, v79
	v_cvt_pk_bf16_f32 v75, v80, v81
	v_cvt_pk_bf16_f32 v76, v84, v85
	v_cvt_pk_bf16_f32 v77, v86, v87
	v_pk_mul_f32 v[72:73], v[72:73], v[170:171] op_sel_hi:[1,0]
	v_pk_mul_f32 v[70:71], v[70:71], v[170:171] op_sel_hi:[1,0]
	v_pk_mul_f32 v[68:69], v[68:69], v[170:171] op_sel_hi:[1,0]
	v_max_f32_e32 v66, 0, v66
	v_max_f32_e32 v67, 0, v67
	global_store_dwordx4 v[82:83], v[74:77], off
	v_max_f32_e32 v70, 0, v70
	v_max_f32_e32 v71, 0, v71
	v_pk_mul_f32 v[74:75], v[66:67], v[66:67]
	v_max_f32_e32 v66, 0, v72
	v_max_f32_e32 v68, 0, v68
	v_max_f32_e32 v67, 0, v73
	v_max_f32_e32 v69, 0, v69
	s_waitcnt lgkmcnt(0)
; __device__ __forceinline__ unsigned pk2(float lo, float hi) { f32x2 v = {lo, hi}; bf16x2_t b = __builtin_convertvector(v, bf16x2_t); return __builtin_bit_cast(unsigned, b); }
; __device__ __forceinline__ void row_rinv8(float (&rs)[8], const float* ssq, int row0, int fq) {
;     ...
;     for (int i = 0; i < 8; ++i) { float s = (pv[i][0] + pv[i][1]) + (pv[i][2] + pv[i][3]); s += __shfl_xor(s, 16); s += __shfl_xor(s, 32); rs[i] = __builtin_amdgcn_rsqf(s * (1.0f / DM) + EPS); }
;     __device__ __forceinline__ void operator()(const Acc& acc, const Unit& u, int wr, int wc, int fr, int fq) const {
;     ...
; #pragma unroll
;         for (int ai = 0; ai < 2; ++ai)
; #pragma unroll
;             for (int m = 0; m < 4; ++m) { bf16_t* rowp = O + (size_t)(row0 + ai * HALF + m * 16) * ldc + col0;
;                 const float rs = rsv[ai * 4 + m];
; #pragma unroll
;                 for (int bj = 0; bj < 2; ++bj) { f32x4 v0 = acc[ai][bj][m][0] * rs, v1 = acc[ai][bj][m][1] * rs;
;                     if (ACT == 1) {
; #pragma unroll
;                         for (int i = 0; i < 4; ++i) { float a = fmaxf(v0[i], 0.f), b = fmaxf(v1[i], 0.f); v0[i] = a * a; v1[i] = b * b; } }
;                     u32x4 w; w.x = pk2(v0[0], v0[1]); w.y = pk2(v0[2], v0[3]); w.z = pk2(v1[0], v1[1]); w.w = pk2(v1[2], v1[3]);
;                     *(u32x4*)(rowp + bj * HALF) = w; } asm volatile("" ::: "memory"); }
	v_add_f32_e32 v138, v138, v139
	v_add_f32_e32 v134, v134, v135
	v_add_f32_e32 v130, v130, v131
	v_pk_mul_f32 v[70:71], v[70:71], v[70:71]
	v_pk_mul_f32 v[72:73], v[66:67], v[66:67]
	v_pk_mul_f32 v[76:77], v[68:69], v[68:69]
	v_pk_mul_f32 v[58:59], v[58:59], v[142:143] op_sel_hi:[1,0]
	v_fmamk_f32 v138, v138, 0x3a800000, v225
	v_mov_b32_e32 v135, v134
	s_nop 1
	v_permlane32_swap_b32_e32 v135, v134
	ds_bpermute_b32 v131, v157, v130
	v_cvt_pk_bf16_f32 v66, v70, v71
	v_cvt_pk_bf16_f32 v67, v72, v73
	v_cvt_pk_bf16_f32 v68, v74, v75
	v_cvt_pk_bf16_f32 v69, v76, v77
	v_pk_mul_f32 v[64:65], v[64:65], v[142:143] op_sel_hi:[1,0]
	v_pk_mul_f32 v[62:63], v[62:63], v[142:143] op_sel_hi:[1,0]
	v_pk_mul_f32 v[60:61], v[60:61], v[142:143] op_sel_hi:[1,0]
	v_max_f32_e32 v58, 0, v58
	v_max_f32_e32 v59, 0, v59
	v_rsq_f32_e32 v138, v138
	global_store_dwordx4 v[82:83], v[66:69], off offset:256
	v_max_f32_e32 v62, 0, v62
	v_max_f32_e32 v63, 0, v63
	v_mad_i64_i32 v[66:67], s[20:21], v162, s0, 0
	v_pk_mul_f32 v[68:69], v[58:59], v[58:59]
	v_max_f32_e32 v58, 0, v64
	v_max_f32_e32 v60, 0, v60
	v_max_f32_e32 v59, 0, v65
	v_max_f32_e32 v61, 0, v61
	v_lshl_add_u64 v[66:67], v[66:67], 1, s[56:57]
	v_pk_mul_f32 v[62:63], v[62:63], v[62:63]
	v_pk_mul_f32 v[64:65], v[58:59], v[58:59]
	v_pk_mul_f32 v[70:71], v[60:61], v[60:61]
	v_pk_mul_f32 v[50:51], v[50:51], v[142:143] op_sel_hi:[1,0]
	v_lshl_add_u64 v[66:67], v[66:67], 0, v[132:133]
	v_cvt_pk_bf16_f32 v58, v62, v63
	v_cvt_pk_bf16_f32 v59, v64, v65
	v_cvt_pk_bf16_f32 v60, v68, v69
	v_cvt_pk_bf16_f32 v61, v70, v71
	v_pk_mul_f32 v[56:57], v[56:57], v[142:143] op_sel_hi:[1,0]
	v_pk_mul_f32 v[54:55], v[54:55], v[142:143] op_sel_hi:[1,0]
	v_pk_mul_f32 v[52:53], v[52:53], v[142:143] op_sel_hi:[1,0]
	v_max_f32_e32 v50, 0, v50
	v_max_f32_e32 v51, 0, v51
	global_store_dwordx4 v[66:67], v[58:61], off
	v_max_f32_e32 v54, 0, v54
	v_max_f32_e32 v55, 0, v55
	v_pk_mul_f32 v[58:59], v[50:51], v[50:51]
	v_max_f32_e32 v50, 0, v56
	v_max_f32_e32 v52, 0, v52
	v_max_f32_e32 v51, 0, v57
	v_max_f32_e32 v53, 0, v53
	s_waitcnt lgkmcnt(0)
	v_add_f32_e32 v134, v134, v135
	v_add_f32_e32 v130, v130, v131
	v_pk_mul_f32 v[54:55], v[54:55], v[54:55]
	v_pk_mul_f32 v[56:57], v[50:51], v[50:51]
	v_pk_mul_f32 v[60:61], v[52:53], v[52:53]
	v_pk_mul_f32 v[42:43], v[42:43], v[138:139] op_sel_hi:[1,0]
	v_fmamk_f32 v134, v134, 0x3a800000, v225
	v_mov_b32_e32 v131, v130
	s_nop 1
	v_permlane32_swap_b32_e32 v131, v130
	v_cvt_pk_bf16_f32 v50, v54, v55
	v_cvt_pk_bf16_f32 v51, v56, v57
	v_cvt_pk_bf16_f32 v52, v58, v59
	v_cvt_pk_bf16_f32 v53, v60, v61
	v_pk_mul_f32 v[48:49], v[48:49], v[138:139] op_sel_hi:[1,0]
	v_pk_mul_f32 v[46:47], v[46:47], v[138:139] op_sel_hi:[1,0]
	v_pk_mul_f32 v[44:45], v[44:45], v[138:139] op_sel_hi:[1,0]
	v_max_f32_e32 v42, 0, v42
	v_max_f32_e32 v43, 0, v43
	v_rsq_f32_e32 v134, v134
	global_store_dwordx4 v[66:67], v[50:53], off offset:256
	v_max_f32_e32 v46, 0, v46
	v_max_f32_e32 v47, 0, v47
	v_mad_i64_i32 v[50:51], s[20:21], v160, s0, 0
	v_pk_mul_f32 v[52:53], v[42:43], v[42:43]
	v_max_f32_e32 v42, 0, v48
	v_max_f32_e32 v44, 0, v44
	v_max_f32_e32 v43, 0, v49
	v_max_f32_e32 v45, 0, v45
	v_lshl_add_u64 v[50:51], v[50:51], 1, s[56:57]
	v_pk_mul_f32 v[46:47], v[46:47], v[46:47]
	v_pk_mul_f32 v[48:49], v[42:43], v[42:43]
	v_pk_mul_f32 v[54:55], v[44:45], v[44:45]
	v_pk_mul_f32 v[34:35], v[34:35], v[138:139] op_sel_hi:[1,0]
	v_lshl_add_u64 v[50:51], v[50:51], 0, v[132:133]
	v_cvt_pk_bf16_f32 v42, v46, v47
	v_cvt_pk_bf16_f32 v43, v48, v49
	v_cvt_pk_bf16_f32 v44, v52, v53
	v_cvt_pk_bf16_f32 v45, v54, v55
	v_pk_mul_f32 v[40:41], v[40:41], v[138:139] op_sel_hi:[1,0]
	v_pk_mul_f32 v[38:39], v[38:39], v[138:139] op_sel_hi:[1,0]
	v_pk_mul_f32 v[36:37], v[36:37], v[138:139] op_sel_hi:[1,0]
	v_max_f32_e32 v34, 0, v34
	v_max_f32_e32 v35, 0, v35
	global_store_dwordx4 v[50:51], v[42:45], off
	v_max_f32_e32 v38, 0, v38
	v_max_f32_e32 v39, 0, v39
	v_pk_mul_f32 v[42:43], v[34:35], v[34:35]
	v_max_f32_e32 v34, 0, v40
	v_max_f32_e32 v36, 0, v36
	v_max_f32_e32 v35, 0, v41
	v_max_f32_e32 v37, 0, v37
	s_waitcnt lgkmcnt(0)
; __device__ __forceinline__ unsigned pk2(float lo, float hi) { f32x2 v = {lo, hi}; bf16x2_t b = __builtin_convertvector(v, bf16x2_t); return __builtin_bit_cast(unsigned, b); }
; #define PG8_BAR __builtin_amdgcn_s_barrier()
;     __device__ __forceinline__ void operator()(const Acc& acc, const Unit& u, int wr, int wc, int fr, int fq) const {
;     ...
; #pragma unroll
;         for (int ai = 0; ai < 2; ++ai)
; #pragma unroll
;             for (int m = 0; m < 4; ++m) { bf16_t* rowp = O + (size_t)(row0 + ai * HALF + m * 16) * ldc + col0;
;                 const float rs = rsv[ai * 4 + m];
; #pragma unroll
;                 for (int bj = 0; bj < 2; ++bj) { f32x4 v0 = acc[ai][bj][m][0] * rs, v1 = acc[ai][bj][m][1] * rs;
;                     if (ACT == 1) {
; #pragma unroll
;                         for (int i = 0; i < 4; ++i) { float a = fmaxf(v0[i], 0.f), b = fmaxf(v1[i], 0.f); v0[i] = a * a; v1[i] = b * b; } }
;                     u32x4 w; w.x = pk2(v0[0], v0[1]); w.y = pk2(v0[2], v0[3]); w.z = pk2(v1[0], v1[1]); w.w = pk2(v1[2], v1[3]);
;                     *(u32x4*)(rowp + bj * HALF) = w; } asm volatile("" ::: "memory"); }
; template <class Epi, class Sched>
; __device__ __forceinline__ void gemm_phase(LAS unsigned char* lds, const Gemm g, const Sched& S, const Epi& E) {
;     ...
;         if (wr == 0) PG8_BAR;
;         { int fr_ = fr, fq_ = fq; asm volatile("" : "+v"(fr_), "+v"(fq_));
;           E(acc, cur, wr, wc, fr_, fq_); }
;         if (!has_next) break;
; #pragma unroll
;         for (int a = 0; a < 2; ++a)
; #pragma unroll
;             for (int b = 0; b < 2; ++b)
; #pragma unroll
;                 for (int m = 0; m < 4; ++m)
; #pragma unroll
;                     for (int n = 0; n < 2; ++n) acc[a][b][m][n] = (f32x4){0.f, 0.f, 0.f, 0.f};
;         cur = nxt; cA = nA; cB = nB; ++ui;
;         if (wr == 1) PG8_BAR;
	v_add_f32_e32 v130, v130, v131
	v_pk_mul_f32 v[38:39], v[38:39], v[38:39]
	v_pk_mul_f32 v[40:41], v[34:35], v[34:35]
	v_pk_mul_f32 v[44:45], v[36:37], v[36:37]
	v_pk_mul_f32 v[26:27], v[26:27], v[134:135] op_sel_hi:[1,0]
	v_fmamk_f32 v130, v130, 0x3a800000, v225
	v_cvt_pk_bf16_f32 v34, v38, v39
	v_cvt_pk_bf16_f32 v35, v40, v41
	v_cvt_pk_bf16_f32 v36, v42, v43
	v_cvt_pk_bf16_f32 v37, v44, v45
	v_pk_mul_f32 v[32:33], v[32:33], v[134:135] op_sel_hi:[1,0]
	v_pk_mul_f32 v[30:31], v[30:31], v[134:135] op_sel_hi:[1,0]
	v_pk_mul_f32 v[28:29], v[28:29], v[134:135] op_sel_hi:[1,0]
	v_max_f32_e32 v26, 0, v26
	v_max_f32_e32 v27, 0, v27
	v_rsq_f32_e32 v130, v130
	global_store_dwordx4 v[50:51], v[34:37], off offset:256
	v_max_f32_e32 v30, 0, v30
	v_max_f32_e32 v31, 0, v31
	v_mad_i64_i32 v[34:35], s[20:21], v158, s0, 0
	v_pk_mul_f32 v[36:37], v[26:27], v[26:27]
	v_max_f32_e32 v26, 0, v32
	v_max_f32_e32 v28, 0, v28
	v_max_f32_e32 v27, 0, v33
	v_max_f32_e32 v29, 0, v29
	v_lshl_add_u64 v[34:35], v[34:35], 1, s[56:57]
	v_pk_mul_f32 v[30:31], v[30:31], v[30:31]
	v_pk_mul_f32 v[32:33], v[26:27], v[26:27]
	v_pk_mul_f32 v[38:39], v[28:29], v[28:29]
	v_pk_mul_f32 v[18:19], v[18:19], v[134:135] op_sel_hi:[1,0]
	v_lshl_add_u64 v[34:35], v[34:35], 0, v[132:133]
	v_cvt_pk_bf16_f32 v26, v30, v31
	v_cvt_pk_bf16_f32 v27, v32, v33
	v_cvt_pk_bf16_f32 v28, v36, v37
	v_cvt_pk_bf16_f32 v29, v38, v39
	v_pk_mul_f32 v[24:25], v[24:25], v[134:135] op_sel_hi:[1,0]
	v_pk_mul_f32 v[22:23], v[22:23], v[134:135] op_sel_hi:[1,0]
	v_pk_mul_f32 v[20:21], v[20:21], v[134:135] op_sel_hi:[1,0]
	v_max_f32_e32 v18, 0, v18
	v_max_f32_e32 v19, 0, v19
	global_store_dwordx4 v[34:35], v[26:29], off
	v_max_f32_e32 v22, 0, v22
	v_max_f32_e32 v23, 0, v23
	v_pk_mul_f32 v[26:27], v[18:19], v[18:19]
	v_max_f32_e32 v18, 0, v24
	v_max_f32_e32 v20, 0, v20
	v_max_f32_e32 v19, 0, v25
	v_max_f32_e32 v21, 0, v21
	v_pk_mul_f32 v[22:23], v[22:23], v[22:23]
	v_pk_mul_f32 v[24:25], v[18:19], v[18:19]
	v_pk_mul_f32 v[28:29], v[20:21], v[20:21]
	v_pk_mul_f32 v[10:11], v[10:11], v[130:131] op_sel_hi:[1,0]
	v_cvt_pk_bf16_f32 v18, v22, v23
	v_cvt_pk_bf16_f32 v19, v24, v25
	v_cvt_pk_bf16_f32 v20, v26, v27
	v_cvt_pk_bf16_f32 v21, v28, v29
	v_pk_mul_f32 v[16:17], v[16:17], v[130:131] op_sel_hi:[1,0]
	v_pk_mul_f32 v[14:15], v[14:15], v[130:131] op_sel_hi:[1,0]
	v_pk_mul_f32 v[12:13], v[12:13], v[130:131] op_sel_hi:[1,0]
	v_max_f32_e32 v10, 0, v10
	v_max_f32_e32 v11, 0, v11
	global_store_dwordx4 v[34:35], v[18:21], off offset:256
	v_max_f32_e32 v14, 0, v14
	v_max_f32_e32 v15, 0, v15
	v_mad_i64_i32 v[18:19], s[0:1], v156, s0, 0
	v_pk_mul_f32 v[20:21], v[10:11], v[10:11]
	v_max_f32_e32 v10, 0, v16
	v_max_f32_e32 v12, 0, v12
	v_max_f32_e32 v11, 0, v17
	v_max_f32_e32 v13, 0, v13
	v_lshl_add_u64 v[18:19], v[18:19], 1, s[56:57]
	v_pk_mul_f32 v[14:15], v[14:15], v[14:15]
	v_pk_mul_f32 v[16:17], v[10:11], v[10:11]
	v_pk_mul_f32 v[22:23], v[12:13], v[12:13]
	v_pk_mul_f32 v[2:3], v[2:3], v[130:131] op_sel_hi:[1,0]
	v_lshl_add_u64 v[18:19], v[18:19], 0, v[132:133]
	v_cvt_pk_bf16_f32 v10, v14, v15
	v_cvt_pk_bf16_f32 v11, v16, v17
	v_cvt_pk_bf16_f32 v12, v20, v21
	v_cvt_pk_bf16_f32 v13, v22, v23
	v_pk_mul_f32 v[8:9], v[8:9], v[130:131] op_sel_hi:[1,0]
	v_pk_mul_f32 v[6:7], v[6:7], v[130:131] op_sel_hi:[1,0]
	v_pk_mul_f32 v[4:5], v[4:5], v[130:131] op_sel_hi:[1,0]
	v_max_f32_e32 v2, 0, v2
	v_max_f32_e32 v3, 0, v3
	global_store_dwordx4 v[18:19], v[10:13], off
	v_max_f32_e32 v6, 0, v6
	v_max_f32_e32 v7, 0, v7
	v_pk_mul_f32 v[10:11], v[2:3], v[2:3]
	v_max_f32_e32 v2, 0, v8
	v_max_f32_e32 v4, 0, v4
	v_max_f32_e32 v3, 0, v9
	v_max_f32_e32 v5, 0, v5
	v_pk_mul_f32 v[6:7], v[6:7], v[6:7]
	v_pk_mul_f32 v[8:9], v[2:3], v[2:3]
	v_pk_mul_f32 v[12:13], v[4:5], v[4:5]
	v_cvt_pk_bf16_f32 v2, v6, v7
	v_cvt_pk_bf16_f32 v3, v8, v9
	v_cvt_pk_bf16_f32 v4, v10, v11
	v_cvt_pk_bf16_f32 v5, v12, v13
	global_store_dwordx4 v[18:19], v[2:5], off offset:256
	s_mov_b64 s[0:1], -1
	s_cbranch_vccnz .LBB0_200
	s_andn2_b64 vcc, exec, s[30:31]
	s_cbranch_vccnz .LBB0_199
	s_barrier
	s_branch .LBB0_199

; __device__ __forceinline__ void row_rinv8(float (&rs)[8], const float* ssq, int row0, int fq) {
;     f32x4 pv[8];
; #pragma unroll
;     for (int i = 0; i < 8; ++i) pv[i] = *(const f32x4*)(ssq + (size_t)(row0 + (i >> 2) * HALF + (i & 3) * 16) * 16 + 4 * fq);
; #pragma unroll
;     for (int i = 0; i < 8; ++i) { float s = (pv[i][0] + pv[i][1]) + (pv[i][2] + pv[i][3]); s += __shfl_xor(s, 16); s += __shfl_xor(s, 32); rs[i] = __builtin_amdgcn_rsqf(s * (1.0f / DM) + EPS); }
; }
;     __device__ __forceinline__ void gate_tile(const Acc& acc, const Unit& u, int wr, int wc, int fr, int fq) const {
;         const int row0 = u.pm * BM + wr * 64 + fr, col0 = u.kind * 1024 + u.pn * BM + wc * 32 + 8 * fq;
;         float rsv[8]; row_rinv8(rsv, ssq, row0, fq);
;         f32x4 bb[2][2];
; #pragma unroll
;         for (int bj = 0; bj < 2; ++bj) { bb[bj][0] = *(const f32x4*)(bg + col0 + bj * HALF); bb[bj][1] = *(const f32x4*)(bg + col0 + bj * HALF + 4); }
; #pragma unroll
;         for (int ai = 0; ai < 2; ++ai)
; #pragma unroll
;             for (int m = 0; m < 4; ++m) { bf16_t* rowp = GT + (size_t)(row0 + ai * HALF + m * 16) * GT_LD + col0; const float rs = rsv[ai * 4 + m];
; #pragma unroll
.LBB0_294:
	s_lshl_b32 s0, s24, 8
	v_mov_b32_e32 v130, v181
	v_mov_b32_e32 v161, v185
	s_add_i32 s0, s0, s77
	s_cmp_eq_u32 s15, 3
	v_add_u32_e32 v146, s0, v130
	s_mov_b64 s[0:1], -1
	s_cbranch_scc1 .LBB0_297
	v_lshlrev_b32_e32 v130, 2, v161
	v_ashrrev_i32_e32 v131, 31, v130
	v_ashrrev_i32_e32 v147, 31, v146
	v_lshl_add_u64 v[164:165], v[130:131], 2, s[54:55]
	v_lshlrev_b64 v[130:131], 6, v[146:147]
	v_lshl_add_u64 v[130:131], v[164:165], 0, v[130:131]
	global_load_dwordx4 v[130:133], v[130:131], off
	v_add_u32_e32 v196, 16, v146
	v_ashrrev_i32_e32 v197, 31, v196
	v_lshlrev_b64 v[134:135], 6, v[196:197]
	v_lshl_add_u64 v[134:135], v[164:165], 0, v[134:135]
	global_load_dwordx4 v[134:137], v[134:135], off
	v_add_u32_e32 v182, 32, v146
	v_ashrrev_i32_e32 v183, 31, v182
	v_lshlrev_b64 v[138:139], 6, v[182:183]
	v_lshl_add_u64 v[138:139], v[164:165], 0, v[138:139]
	global_load_dwordx4 v[138:141], v[138:139], off
	v_add_u32_e32 v178, 48, v146
	v_ashrrev_i32_e32 v179, 31, v178
	v_lshlrev_b64 v[142:143], 6, v[178:179]
	v_lshl_add_u64 v[142:143], v[164:165], 0, v[142:143]
	global_load_dwordx4 v[142:145], v[142:143], off
	v_add_u32_e32 v170, 0x80, v146
	v_ashrrev_i32_e32 v171, 31, v170
	v_lshlrev_b64 v[148:149], 6, v[170:171]
	v_lshl_add_u64 v[148:149], v[164:165], 0, v[148:149]
	global_load_dwordx4 v[172:175], v[148:149], off
	v_add_u32_e32 v166, 0x90, v146
	v_ashrrev_i32_e32 v167, 31, v166
	v_lshlrev_b64 v[148:149], 6, v[166:167]
	v_add_u32_e32 v162, 0xa0, v146
	v_lshl_add_u64 v[148:149], v[164:165], 0, v[148:149]
	v_ashrrev_i32_e32 v163, 31, v162
	global_load_dwordx4 v[202:205], v[148:149], off
	v_lshlrev_b64 v[148:149], 6, v[162:163]
	v_lshl_add_u64 v[148:149], v[164:165], 0, v[148:149]
	global_load_dwordx4 v[206:209], v[148:149], off
	v_add_u32_e32 v148, 0xb0, v146
	v_ashrrev_i32_e32 v149, 31, v148
	v_lshlrev_b64 v[168:169], 6, v[148:149]
	v_and_b32_e32 v149, 64, v224
	v_lshl_add_u64 v[164:165], v[164:165], 0, v[168:169]
	v_xor_b32_e32 v147, 16, v224
	v_add_u32_e32 v149, 64, v149
	global_load_dwordx4 v[210:213], v[164:165], off
	v_cmp_lt_i32_e32 vcc, v147, v149
	v_xor_b32_e32 v160, 32, v224
	s_lshl_b32 s0, s15, 10
	v_cndmask_b32_e32 v147, v224, v147, vcc
	v_lshlrev_b32_e32 v147, 2, v147
	v_cmp_lt_i32_e32 vcc, v160, v149
	s_lshl_b32 s1, s14, 8
	s_or_b32 s0, s0, s96
	v_cndmask_b32_e32 v149, v224, v160, vcc
	v_lshlrev_b32_e32 v149, 2, v149
	s_add_i32 s0, s0, s1
	v_lshl_add_u32 v176, v161, 3, s0
	v_ashrrev_i32_e32 v177, 31, v176
	s_waitcnt vmcnt(0) lgkmcnt(0)
	v_add_f32_e32 v131, v131, v130
	v_add_f32_e32 v132, v132, v133
	v_add_f32_e32 v130, v131, v132
	v_add_f32_e32 v135, v135, v134
	v_add_f32_e32 v136, v136, v137
	v_add_f32_e32 v134, v135, v136
	v_add_f32_e32 v139, v139, v138
	v_add_f32_e32 v140, v140, v141
	v_add_f32_e32 v138, v139, v140
	v_add_f32_e32 v143, v143, v142
	v_add_f32_e32 v144, v144, v145
	v_add_f32_e32 v142, v143, v144
	v_add_f32_e32 v173, v173, v172
	v_add_f32_e32 v174, v174, v175
	v_add_f32_e32 v172, v173, v174
	v_add_f32_e32 v203, v203, v202
	v_add_f32_e32 v204, v204, v205
	v_add_f32_e32 v202, v203, v204
	v_add_f32_e32 v207, v207, v206
	v_add_f32_e32 v208, v208, v209
	v_add_f32_e32 v206, v207, v208
	v_add_f32_e32 v211, v211, v210
	v_add_f32_e32 v212, v212, v213
	v_add_f32_e32 v210, v211, v212
	ds_bpermute_b32 v131, v147, v130
	ds_bpermute_b32 v135, v147, v134
	ds_bpermute_b32 v139, v147, v138
	ds_bpermute_b32 v143, v147, v142
	ds_bpermute_b32 v173, v147, v172
	ds_bpermute_b32 v203, v147, v202
	ds_bpermute_b32 v207, v147, v206
	ds_bpermute_b32 v211, v147, v210
	s_waitcnt lgkmcnt(0)
	v_add_f32_e32 v130, v130, v131
	v_add_f32_e32 v134, v134, v135
	v_add_f32_e32 v138, v138, v139
	v_add_f32_e32 v142, v142, v143
	v_add_f32_e32 v172, v172, v173
	v_add_f32_e32 v202, v202, v203
	v_add_f32_e32 v206, v206, v207
	v_add_f32_e32 v210, v210, v211
	v_mov_b32_e32 v131, v130
	s_nop 1
	v_permlane32_swap_b32_e32 v131, v130
	v_mov_b32_e32 v135, v134
	s_nop 1
	v_permlane32_swap_b32_e32 v135, v134
	v_mov_b32_e32 v139, v138
	s_nop 1
	v_permlane32_swap_b32_e32 v139, v138
	v_mov_b32_e32 v143, v142
	s_nop 1
	v_permlane32_swap_b32_e32 v143, v142
	v_mov_b32_e32 v173, v172
	s_nop 1
	v_permlane32_swap_b32_e32 v173, v172
	v_mov_b32_e32 v203, v202
	s_nop 1
	v_permlane32_swap_b32_e32 v203, v202
	v_mov_b32_e32 v207, v206
	s_nop 1
	v_permlane32_swap_b32_e32 v207, v206
	v_mov_b32_e32 v211, v210
	s_nop 1
	v_permlane32_swap_b32_e32 v211, v210
	s_waitcnt lgkmcnt(0)
	v_add_f32_e32 v130, v130, v131
	v_add_f32_e32 v134, v134, v135
	v_add_f32_e32 v138, v138, v139
	v_add_f32_e32 v142, v142, v143
	v_add_f32_e32 v172, v172, v173
	v_add_f32_e32 v202, v202, v203
	v_add_f32_e32 v206, v206, v207
	v_add_f32_e32 v210, v210, v211
	v_fmamk_f32 v130, v130, 0x3a800000, v225
	v_fmamk_f32 v134, v134, 0x3a800000, v225
	v_fmamk_f32 v138, v138, 0x3a800000, v225
	v_fmamk_f32 v142, v142, 0x3a800000, v225
	v_fmamk_f32 v172, v172, 0x3a800000, v225
	v_fmamk_f32 v202, v202, 0x3a800000, v225
	v_fmamk_f32 v206, v206, 0x3a800000, v225
	v_fmamk_f32 v210, v210, 0x3a800000, v225
	v_rsq_f32_e32 v200, v130
	v_rsq_f32_e32 v198, v134
	v_rsq_f32_e32 v184, v138
	v_rsq_f32_e32 v180, v142
	v_rsq_f32_e32 v172, v172
	v_rsq_f32_e32 v168, v202
	v_rsq_f32_e32 v164, v206
	v_rsq_f32_e32 v160, v210
	s_nop 0
	v_lshl_add_u64 v[142:143], v[176:177], 2, s[58:59]
	v_lshlrev_b64 v[176:177], 1, v[176:177]
	v_mov_b64_e32 v[174:175], s[56:57]
	v_mad_i64_i32 v[196:197], s[0:1], v196, s33, v[174:175]
	v_lshl_add_u64 v[196:197], v[196:197], 0, v[176:177]
	v_mad_i64_i32 v[182:183], s[0:1], v182, s33, v[174:175]
	v_lshl_add_u64 v[182:183], v[182:183], 0, v[176:177]
	v_mad_i64_i32 v[178:179], s[0:1], v178, s33, v[174:175]
	v_lshl_add_u64 v[178:179], v[178:179], 0, v[176:177]
	v_pk_mul_f32 v[204:205], v[128:129], v[200:201] op_sel_hi:[1,0]
	v_mad_i64_i32 v[202:203], s[0:1], v146, s33, v[174:175]
	v_lshl_add_u64 v[202:203], v[202:203], 0, v[176:177]
	v_pk_mul_f32 v[206:207], v[126:127], v[200:201] op_sel_hi:[1,0]
	v_pk_mul_f32 v[208:209], v[124:125], v[200:201] op_sel_hi:[1,0]
	v_pk_mul_f32 v[210:211], v[122:123], v[200:201] op_sel_hi:[1,0]
	global_load_dwordx4 v[134:137], v[142:143], off offset:16
	global_load_dwordx4 v[138:141], v[142:143], off
	global_load_dwordx4 v[130:133], v[142:143], off offset:528
	s_nop 0
	global_load_dwordx4 v[142:145], v[142:143], off offset:512
	s_waitcnt vmcnt(3)
; __device__ __forceinline__ unsigned pk2(float lo, float hi) { f32x2 v = {lo, hi}; bf16x2_t b = __builtin_convertvector(v, bf16x2_t); return __builtin_bit_cast(unsigned, b); }
; __device__ __forceinline__ float sigmoidf_(float x) { return __builtin_amdgcn_rcpf(1.0f + __builtin_amdgcn_exp2f(-1.4426950408889634f * x)); }
;     __device__ __forceinline__ void gate_tile(const Acc& acc, const Unit& u, int wr, int wc, int fr, int fq) const {
;     ...
;                 for (int bj = 0; bj < 2; ++bj) { f32x4 v0 = acc[ai][bj][m][0] * rs, v1 = acc[ai][bj][m][1] * rs;
; #pragma unroll
;                     for (int i = 0; i < 4; ++i) { v0[i] = sigmoidf_(v0[i] + bb[bj][0][i]); v1[i] = sigmoidf_(v1[i] + bb[bj][1][i]); }
;                     u32x4 w; w.x = pk2(v0[0], v0[1]); w.y = pk2(v0[2], v0[3]); w.z = pk2(v1[0], v1[1]); w.w = pk2(v1[2], v1[3]);
;                     *(u32x4*)(rowp + bj * HALF) = w; } asm volatile("" ::: "memory"); }
	v_add_f32_e32 v149, v210, v134
	s_waitcnt vmcnt(2)
	v_add_f32_e32 v147, v206, v138
	v_add_f32_e32 v163, v207, v139
	v_add_f32_e32 v165, v211, v135
	v_add_f32_e32 v167, v204, v140
	v_add_f32_e32 v169, v208, v136
	v_add_f32_e32 v171, v205, v141
	v_add_f32_e32 v173, v209, v137
	v_mul_f32_e32 v147, 0xbfb8aa3b, v147
	v_mul_f32_e32 v149, 0xbfb8aa3b, v149
	v_mul_f32_e32 v163, 0xbfb8aa3b, v163
	v_mul_f32_e32 v165, 0xbfb8aa3b, v165
	v_mul_f32_e32 v167, 0xbfb8aa3b, v167
	v_mul_f32_e32 v169, 0xbfb8aa3b, v169
	v_mul_f32_e32 v171, 0xbfb8aa3b, v171
	v_mul_f32_e32 v173, 0xbfb8aa3b, v173
	v_exp_f32_e32 v147, v147
	v_exp_f32_e32 v149, v149
	v_exp_f32_e32 v163, v163
	v_exp_f32_e32 v165, v165
	v_exp_f32_e32 v167, v167
	v_exp_f32_e32 v169, v169
	v_exp_f32_e32 v171, v171
	v_exp_f32_e32 v173, v173
	v_add_f32_e32 v147, 1.0, v147
	v_add_f32_e32 v149, 1.0, v149
	v_add_f32_e32 v163, 1.0, v163
	v_add_f32_e32 v165, 1.0, v165
	v_add_f32_e32 v167, 1.0, v167
	v_add_f32_e32 v169, 1.0, v169
	v_add_f32_e32 v171, 1.0, v171
	v_add_f32_e32 v173, 1.0, v173
	v_rcp_f32_e32 v147, v147
	v_rcp_f32_e32 v149, v149
	v_rcp_f32_e32 v163, v163
	v_rcp_f32_e32 v165, v165
	v_rcp_f32_e32 v167, v167
	v_rcp_f32_e32 v169, v169
	v_rcp_f32_e32 v171, v171
	v_rcp_f32_e32 v173, v173
	v_cvt_pk_bf16_f32 v204, v147, v163
	v_cvt_pk_bf16_f32 v206, v149, v165
	v_cvt_pk_bf16_f32 v205, v167, v171
	v_cvt_pk_bf16_f32 v207, v169, v173
	global_store_dwordx4 v[202:203], v[204:207], off
	v_pk_mul_f32 v[208:209], v[60:61], v[200:201] op_sel_hi:[1,0]
	s_nop 0
	v_pk_mul_f32 v[204:205], v[64:65], v[200:201] op_sel_hi:[1,0]
	v_pk_mul_f32 v[206:207], v[62:63], v[200:201] op_sel_hi:[1,0]
	v_pk_mul_f32 v[200:201], v[58:59], v[200:201] op_sel_hi:[1,0]
	s_waitcnt vmcnt(0)
	v_add_f32_e32 v147, v206, v142
	v_add_f32_e32 v149, v200, v130
	v_add_f32_e32 v163, v207, v143
	v_add_f32_e32 v165, v201, v131
	v_add_f32_e32 v167, v204, v144
	v_add_f32_e32 v169, v208, v132
	v_add_f32_e32 v171, v205, v145
	v_add_f32_e32 v173, v209, v133
	v_mul_f32_e32 v147, 0xbfb8aa3b, v147
	v_mul_f32_e32 v149, 0xbfb8aa3b, v149
	v_mul_f32_e32 v163, 0xbfb8aa3b, v163
	v_mul_f32_e32 v165, 0xbfb8aa3b, v165
	v_mul_f32_e32 v167, 0xbfb8aa3b, v167
	v_mul_f32_e32 v169, 0xbfb8aa3b, v169
	v_mul_f32_e32 v171, 0xbfb8aa3b, v171
	v_mul_f32_e32 v173, 0xbfb8aa3b, v173
	v_exp_f32_e32 v147, v147
	v_exp_f32_e32 v149, v149
	v_exp_f32_e32 v163, v163
	v_exp_f32_e32 v165, v165
	v_exp_f32_e32 v167, v167
	v_exp_f32_e32 v169, v169
	v_exp_f32_e32 v171, v171
	v_exp_f32_e32 v173, v173
	v_add_f32_e32 v147, 1.0, v147
	v_add_f32_e32 v149, 1.0, v149
	v_add_f32_e32 v163, 1.0, v163
	v_add_f32_e32 v165, 1.0, v165
	v_add_f32_e32 v167, 1.0, v167
	v_add_f32_e32 v169, 1.0, v169
	v_add_f32_e32 v171, 1.0, v171
	v_add_f32_e32 v173, 1.0, v173
	v_rcp_f32_e32 v147, v147
	v_rcp_f32_e32 v149, v149
	v_rcp_f32_e32 v163, v163
	v_rcp_f32_e32 v165, v165
	v_rcp_f32_e32 v167, v167
	v_rcp_f32_e32 v169, v169
	v_rcp_f32_e32 v171, v171
	v_rcp_f32_e32 v173, v173
	v_cvt_pk_bf16_f32 v204, v147, v163
	v_cvt_pk_bf16_f32 v206, v149, v165
	v_cvt_pk_bf16_f32 v205, v167, v171
	v_cvt_pk_bf16_f32 v207, v169, v173
	global_store_dwordx4 v[202:203], v[204:207], off offset:256
	v_pk_mul_f32 v[200:201], v[120:121], v[198:199] op_sel_hi:[1,0]
	v_pk_mul_f32 v[202:203], v[118:119], v[198:199] op_sel_hi:[1,0]
	v_pk_mul_f32 v[204:205], v[116:117], v[198:199] op_sel_hi:[1,0]
	v_pk_mul_f32 v[206:207], v[114:115], v[198:199] op_sel_hi:[1,0]
	v_add_f32_e32 v147, v202, v138
	v_add_f32_e32 v149, v206, v134
	v_add_f32_e32 v163, v203, v139
	v_add_f32_e32 v165, v207, v135
	v_add_f32_e32 v167, v200, v140
	v_add_f32_e32 v169, v204, v136
	v_add_f32_e32 v171, v201, v141
	v_add_f32_e32 v173, v205, v137
	v_mul_f32_e32 v147, 0xbfb8aa3b, v147
	v_mul_f32_e32 v149, 0xbfb8aa3b, v149
	v_mul_f32_e32 v163, 0xbfb8aa3b, v163
	v_mul_f32_e32 v165, 0xbfb8aa3b, v165
	v_mul_f32_e32 v167, 0xbfb8aa3b, v167
	v_mul_f32_e32 v169, 0xbfb8aa3b, v169
	v_mul_f32_e32 v171, 0xbfb8aa3b, v171
	v_mul_f32_e32 v173, 0xbfb8aa3b, v173
	v_exp_f32_e32 v147, v147
	v_exp_f32_e32 v149, v149
	v_exp_f32_e32 v163, v163
	v_exp_f32_e32 v165, v165
	v_exp_f32_e32 v167, v167
	v_exp_f32_e32 v169, v169
	v_exp_f32_e32 v171, v171
	v_exp_f32_e32 v173, v173
	v_add_f32_e32 v147, 1.0, v147
	v_add_f32_e32 v149, 1.0, v149
	v_add_f32_e32 v163, 1.0, v163
	v_add_f32_e32 v165, 1.0, v165
	v_add_f32_e32 v167, 1.0, v167
	v_add_f32_e32 v169, 1.0, v169
	v_add_f32_e32 v171, 1.0, v171
	v_add_f32_e32 v173, 1.0, v173
	v_rcp_f32_e32 v147, v147
	v_rcp_f32_e32 v149, v149
	v_rcp_f32_e32 v163, v163
	v_rcp_f32_e32 v165, v165
	v_rcp_f32_e32 v167, v167
	v_rcp_f32_e32 v169, v169
	v_rcp_f32_e32 v171, v171
	v_rcp_f32_e32 v173, v173
	v_cvt_pk_bf16_f32 v200, v147, v163
	v_cvt_pk_bf16_f32 v202, v149, v165
	v_cvt_pk_bf16_f32 v201, v167, v171
	v_cvt_pk_bf16_f32 v203, v169, v173
	global_store_dwordx4 v[196:197], v[200:203], off
	v_pk_mul_f32 v[204:205], v[52:53], v[198:199] op_sel_hi:[1,0]
	v_pk_mul_f32 v[206:207], v[50:51], v[198:199] op_sel_hi:[1,0]
	v_pk_mul_f32 v[200:201], v[56:57], v[198:199] op_sel_hi:[1,0]
	v_pk_mul_f32 v[202:203], v[54:55], v[198:199] op_sel_hi:[1,0]
	v_add_f32_e32 v149, v206, v130
	v_add_f32_e32 v147, v202, v142
	v_add_f32_e32 v163, v203, v143
	v_add_f32_e32 v165, v207, v131
	v_add_f32_e32 v167, v200, v144
	v_add_f32_e32 v169, v204, v132
	v_add_f32_e32 v171, v201, v145
	v_add_f32_e32 v173, v205, v133
	v_mul_f32_e32 v147, 0xbfb8aa3b, v147
	v_mul_f32_e32 v149, 0xbfb8aa3b, v149
	v_mul_f32_e32 v163, 0xbfb8aa3b, v163
	v_mul_f32_e32 v165, 0xbfb8aa3b, v165
	v_mul_f32_e32 v167, 0xbfb8aa3b, v167
	v_mul_f32_e32 v169, 0xbfb8aa3b, v169
	v_mul_f32_e32 v171, 0xbfb8aa3b, v171
	v_mul_f32_e32 v173, 0xbfb8aa3b, v173
; __device__ __forceinline__ unsigned pk2(float lo, float hi) { f32x2 v = {lo, hi}; bf16x2_t b = __builtin_convertvector(v, bf16x2_t); return __builtin_bit_cast(unsigned, b); }
; __device__ __forceinline__ float sigmoidf_(float x) { return __builtin_amdgcn_rcpf(1.0f + __builtin_amdgcn_exp2f(-1.4426950408889634f * x)); }
;     __device__ __forceinline__ void gate_tile(const Acc& acc, const Unit& u, int wr, int wc, int fr, int fq) const {
;     ...
;                 for (int bj = 0; bj < 2; ++bj) { f32x4 v0 = acc[ai][bj][m][0] * rs, v1 = acc[ai][bj][m][1] * rs;
; #pragma unroll
;                     for (int i = 0; i < 4; ++i) { v0[i] = sigmoidf_(v0[i] + bb[bj][0][i]); v1[i] = sigmoidf_(v1[i] + bb[bj][1][i]); }
;                     u32x4 w; w.x = pk2(v0[0], v0[1]); w.y = pk2(v0[2], v0[3]); w.z = pk2(v1[0], v1[1]); w.w = pk2(v1[2], v1[3]);
;                     *(u32x4*)(rowp + bj * HALF) = w; } asm volatile("" ::: "memory"); }
	v_exp_f32_e32 v147, v147
	v_exp_f32_e32 v149, v149
	v_exp_f32_e32 v163, v163
	v_exp_f32_e32 v165, v165
	v_exp_f32_e32 v167, v167
	v_exp_f32_e32 v169, v169
	v_exp_f32_e32 v171, v171
	v_exp_f32_e32 v173, v173
	v_add_f32_e32 v147, 1.0, v147
	v_add_f32_e32 v149, 1.0, v149
	v_add_f32_e32 v163, 1.0, v163
	v_add_f32_e32 v165, 1.0, v165
	v_add_f32_e32 v167, 1.0, v167
	v_add_f32_e32 v169, 1.0, v169
	v_add_f32_e32 v171, 1.0, v171
	v_add_f32_e32 v173, 1.0, v173
	v_rcp_f32_e32 v147, v147
	v_rcp_f32_e32 v149, v149
	v_rcp_f32_e32 v163, v163
	v_rcp_f32_e32 v165, v165
	v_rcp_f32_e32 v167, v167
	v_rcp_f32_e32 v169, v169
	v_rcp_f32_e32 v171, v171
	v_rcp_f32_e32 v173, v173
	v_cvt_pk_bf16_f32 v200, v147, v163
	v_cvt_pk_bf16_f32 v202, v149, v165
	v_cvt_pk_bf16_f32 v201, v167, v171
	v_cvt_pk_bf16_f32 v203, v169, v173
	global_store_dwordx4 v[196:197], v[200:203], off offset:256
	v_pk_mul_f32 v[196:197], v[112:113], v[184:185] op_sel_hi:[1,0]
	v_pk_mul_f32 v[204:205], v[106:107], v[184:185] op_sel_hi:[1,0]
	v_pk_mul_f32 v[200:201], v[110:111], v[184:185] op_sel_hi:[1,0]
	v_pk_mul_f32 v[202:203], v[108:109], v[184:185] op_sel_hi:[1,0]
	v_add_f32_e32 v147, v200, v138
	v_add_f32_e32 v149, v204, v134
	v_add_f32_e32 v163, v201, v139
	v_add_f32_e32 v165, v205, v135
	v_add_f32_e32 v167, v196, v140
	v_add_f32_e32 v169, v202, v136
	v_add_f32_e32 v171, v197, v141
	v_add_f32_e32 v173, v203, v137
	v_mul_f32_e32 v147, 0xbfb8aa3b, v147
	v_mul_f32_e32 v149, 0xbfb8aa3b, v149
	v_mul_f32_e32 v163, 0xbfb8aa3b, v163
	v_mul_f32_e32 v165, 0xbfb8aa3b, v165
	v_mul_f32_e32 v167, 0xbfb8aa3b, v167
	v_mul_f32_e32 v169, 0xbfb8aa3b, v169
	v_mul_f32_e32 v171, 0xbfb8aa3b, v171
	v_mul_f32_e32 v173, 0xbfb8aa3b, v173
	v_exp_f32_e32 v147, v147
	v_exp_f32_e32 v149, v149
	v_exp_f32_e32 v163, v163
	v_exp_f32_e32 v165, v165
	v_exp_f32_e32 v167, v167
	v_exp_f32_e32 v169, v169
	v_exp_f32_e32 v171, v171
	v_exp_f32_e32 v173, v173
	v_add_f32_e32 v147, 1.0, v147
	v_add_f32_e32 v149, 1.0, v149
	v_add_f32_e32 v163, 1.0, v163
	v_add_f32_e32 v165, 1.0, v165
	v_add_f32_e32 v167, 1.0, v167
	v_add_f32_e32 v169, 1.0, v169
	v_add_f32_e32 v171, 1.0, v171
	v_add_f32_e32 v173, 1.0, v173
	v_rcp_f32_e32 v147, v147
	v_rcp_f32_e32 v149, v149
	v_rcp_f32_e32 v163, v163
	v_rcp_f32_e32 v165, v165
	v_rcp_f32_e32 v167, v167
	v_rcp_f32_e32 v169, v169
	v_rcp_f32_e32 v171, v171
	v_rcp_f32_e32 v173, v173
	v_cvt_pk_bf16_f32 v200, v147, v163
	v_cvt_pk_bf16_f32 v202, v149, v165
	v_cvt_pk_bf16_f32 v201, v167, v171
	v_cvt_pk_bf16_f32 v203, v169, v173
	global_store_dwordx4 v[182:183], v[200:203], off
	v_pk_mul_f32 v[196:197], v[48:49], v[184:185] op_sel_hi:[1,0]
	v_pk_mul_f32 v[204:205], v[42:43], v[184:185] op_sel_hi:[1,0]
	v_pk_mul_f32 v[200:201], v[46:47], v[184:185] op_sel_hi:[1,0]
	v_pk_mul_f32 v[202:203], v[44:45], v[184:185] op_sel_hi:[1,0]
	v_add_f32_e32 v147, v200, v142
	v_add_f32_e32 v149, v204, v130
	v_add_f32_e32 v163, v201, v143
	v_add_f32_e32 v165, v205, v131
	v_add_f32_e32 v167, v196, v144
	v_add_f32_e32 v169, v202, v132
	v_add_f32_e32 v171, v197, v145
	v_add_f32_e32 v173, v203, v133
	v_mul_f32_e32 v147, 0xbfb8aa3b, v147
	v_mul_f32_e32 v149, 0xbfb8aa3b, v149
	v_mul_f32_e32 v163, 0xbfb8aa3b, v163
	v_mul_f32_e32 v165, 0xbfb8aa3b, v165
	v_mul_f32_e32 v167, 0xbfb8aa3b, v167
	v_mul_f32_e32 v169, 0xbfb8aa3b, v169
	v_mul_f32_e32 v171, 0xbfb8aa3b, v171
	v_mul_f32_e32 v173, 0xbfb8aa3b, v173
	v_exp_f32_e32 v147, v147
	v_exp_f32_e32 v149, v149
	v_exp_f32_e32 v163, v163
	v_exp_f32_e32 v165, v165
	v_exp_f32_e32 v167, v167
	v_exp_f32_e32 v169, v169
	v_exp_f32_e32 v171, v171
	v_exp_f32_e32 v173, v173
	v_add_f32_e32 v147, 1.0, v147
	v_add_f32_e32 v149, 1.0, v149
	v_add_f32_e32 v163, 1.0, v163
	v_add_f32_e32 v165, 1.0, v165
	v_add_f32_e32 v167, 1.0, v167
	v_add_f32_e32 v169, 1.0, v169
	v_add_f32_e32 v171, 1.0, v171
	v_add_f32_e32 v173, 1.0, v173
	v_rcp_f32_e32 v147, v147
	v_rcp_f32_e32 v149, v149
	v_rcp_f32_e32 v163, v163
	v_rcp_f32_e32 v165, v165
	v_rcp_f32_e32 v167, v167
	v_rcp_f32_e32 v169, v169
	v_rcp_f32_e32 v171, v171
	v_rcp_f32_e32 v173, v173
	v_cvt_pk_bf16_f32 v200, v147, v163
	v_cvt_pk_bf16_f32 v202, v149, v165
	v_cvt_pk_bf16_f32 v201, v167, v171
	v_cvt_pk_bf16_f32 v203, v169, v173
	global_store_dwordx4 v[182:183], v[200:203], off offset:256
	v_pk_mul_f32 v[182:183], v[104:105], v[180:181] op_sel_hi:[1,0]
	v_pk_mul_f32 v[196:197], v[102:103], v[180:181] op_sel_hi:[1,0]
	v_pk_mul_f32 v[200:201], v[100:101], v[180:181] op_sel_hi:[1,0]
	v_pk_mul_f32 v[202:203], v[98:99], v[180:181] op_sel_hi:[1,0]
	v_add_f32_e32 v147, v196, v138
	v_add_f32_e32 v149, v202, v134
	v_add_f32_e32 v163, v197, v139
	v_add_f32_e32 v165, v203, v135
	v_add_f32_e32 v167, v182, v140
	v_add_f32_e32 v169, v200, v136
	v_add_f32_e32 v171, v183, v141
	v_add_f32_e32 v173, v201, v137
	v_mul_f32_e32 v147, 0xbfb8aa3b, v147
	v_mul_f32_e32 v149, 0xbfb8aa3b, v149
	v_mul_f32_e32 v163, 0xbfb8aa3b, v163
	v_mul_f32_e32 v165, 0xbfb8aa3b, v165
	v_mul_f32_e32 v167, 0xbfb8aa3b, v167
	v_mul_f32_e32 v169, 0xbfb8aa3b, v169
	v_mul_f32_e32 v171, 0xbfb8aa3b, v171
	v_mul_f32_e32 v173, 0xbfb8aa3b, v173
	v_exp_f32_e32 v147, v147
	v_exp_f32_e32 v149, v149
	v_exp_f32_e32 v163, v163
	v_exp_f32_e32 v165, v165
	v_exp_f32_e32 v167, v167
	v_exp_f32_e32 v169, v169
	v_exp_f32_e32 v171, v171
	v_exp_f32_e32 v173, v173
	v_add_f32_e32 v147, 1.0, v147
	v_add_f32_e32 v149, 1.0, v149
	v_add_f32_e32 v163, 1.0, v163
	v_add_f32_e32 v165, 1.0, v165
	v_add_f32_e32 v167, 1.0, v167
	v_add_f32_e32 v169, 1.0, v169
	v_add_f32_e32 v171, 1.0, v171
	v_add_f32_e32 v173, 1.0, v173
	v_rcp_f32_e32 v147, v147
	v_rcp_f32_e32 v149, v149
	v_rcp_f32_e32 v163, v163
	v_rcp_f32_e32 v165, v165
	v_rcp_f32_e32 v167, v167
; __device__ __forceinline__ unsigned pk2(float lo, float hi) { f32x2 v = {lo, hi}; bf16x2_t b = __builtin_convertvector(v, bf16x2_t); return __builtin_bit_cast(unsigned, b); }
; __device__ __forceinline__ float sigmoidf_(float x) { return __builtin_amdgcn_rcpf(1.0f + __builtin_amdgcn_exp2f(-1.4426950408889634f * x)); }
;     __device__ __forceinline__ void gate_tile(const Acc& acc, const Unit& u, int wr, int wc, int fr, int fq) const {
;     ...
;             for (int m = 0; m < 4; ++m) { bf16_t* rowp = GT + (size_t)(row0 + ai * HALF + m * 16) * GT_LD + col0; const float rs = rsv[ai * 4 + m];
; #pragma unroll
;                 for (int bj = 0; bj < 2; ++bj) { f32x4 v0 = acc[ai][bj][m][0] * rs, v1 = acc[ai][bj][m][1] * rs;
; #pragma unroll
;                     for (int i = 0; i < 4; ++i) { v0[i] = sigmoidf_(v0[i] + bb[bj][0][i]); v1[i] = sigmoidf_(v1[i] + bb[bj][1][i]); }
;                     u32x4 w; w.x = pk2(v0[0], v0[1]); w.y = pk2(v0[2], v0[3]); w.z = pk2(v1[0], v1[1]); w.w = pk2(v1[2], v1[3]);
;                     *(u32x4*)(rowp + bj * HALF) = w; } asm volatile("" ::: "memory"); }
	v_rcp_f32_e32 v169, v169
	v_rcp_f32_e32 v171, v171
	v_rcp_f32_e32 v173, v173
	v_cvt_pk_bf16_f32 v200, v147, v163
	v_cvt_pk_bf16_f32 v202, v149, v165
	v_cvt_pk_bf16_f32 v201, v167, v171
	v_cvt_pk_bf16_f32 v203, v169, v173
	global_store_dwordx4 v[178:179], v[200:203], off
	v_pk_mul_f32 v[182:183], v[40:41], v[180:181] op_sel_hi:[1,0]
	v_pk_mul_f32 v[196:197], v[38:39], v[180:181] op_sel_hi:[1,0]
	v_pk_mul_f32 v[200:201], v[36:37], v[180:181] op_sel_hi:[1,0]
	v_pk_mul_f32 v[202:203], v[34:35], v[180:181] op_sel_hi:[1,0]
	v_add_f32_e32 v147, v196, v142
	v_add_f32_e32 v149, v202, v130
	v_add_f32_e32 v163, v197, v143
	v_add_f32_e32 v165, v203, v131
	v_add_f32_e32 v167, v182, v144
	v_add_f32_e32 v169, v200, v132
	v_add_f32_e32 v171, v183, v145
	v_add_f32_e32 v173, v201, v133
	v_mul_f32_e32 v147, 0xbfb8aa3b, v147
	v_mul_f32_e32 v149, 0xbfb8aa3b, v149
	v_mul_f32_e32 v163, 0xbfb8aa3b, v163
	v_mul_f32_e32 v165, 0xbfb8aa3b, v165
	v_mul_f32_e32 v167, 0xbfb8aa3b, v167
	v_mul_f32_e32 v169, 0xbfb8aa3b, v169
	v_mul_f32_e32 v171, 0xbfb8aa3b, v171
	v_mul_f32_e32 v173, 0xbfb8aa3b, v173
	v_exp_f32_e32 v147, v147
	v_exp_f32_e32 v149, v149
	v_exp_f32_e32 v163, v163
	v_exp_f32_e32 v165, v165
	v_exp_f32_e32 v167, v167
	v_exp_f32_e32 v169, v169
	v_exp_f32_e32 v171, v171
	v_exp_f32_e32 v173, v173
	v_add_f32_e32 v147, 1.0, v147
	v_add_f32_e32 v149, 1.0, v149
	v_add_f32_e32 v163, 1.0, v163
	v_add_f32_e32 v165, 1.0, v165
	v_add_f32_e32 v167, 1.0, v167
	v_add_f32_e32 v169, 1.0, v169
	v_add_f32_e32 v171, 1.0, v171
	v_add_f32_e32 v173, 1.0, v173
	v_rcp_f32_e32 v147, v147
	v_rcp_f32_e32 v149, v149
	v_rcp_f32_e32 v163, v163
	v_rcp_f32_e32 v165, v165
	v_rcp_f32_e32 v167, v167
	v_rcp_f32_e32 v169, v169
	v_rcp_f32_e32 v171, v171
	v_rcp_f32_e32 v173, v173
	v_cvt_pk_bf16_f32 v200, v147, v163
	v_cvt_pk_bf16_f32 v202, v149, v165
	v_cvt_pk_bf16_f32 v201, v167, v171
	v_cvt_pk_bf16_f32 v203, v169, v173
	global_store_dwordx4 v[178:179], v[200:203], off offset:256
	v_pk_mul_f32 v[178:179], v[96:97], v[172:173] op_sel_hi:[1,0]
	v_pk_mul_f32 v[196:197], v[92:93], v[172:173] op_sel_hi:[1,0]
	v_pk_mul_f32 v[182:183], v[94:95], v[172:173] op_sel_hi:[1,0]
	v_pk_mul_f32 v[200:201], v[90:91], v[172:173] op_sel_hi:[1,0]
	v_add_f32_e32 v167, v140, v178
	v_add_f32_e32 v169, v136, v196
	v_add_f32_e32 v173, v141, v179
	v_add_f32_e32 v178, v137, v197
	v_add_f32_e32 v147, v138, v182
	v_add_f32_e32 v149, v134, v200
	v_add_f32_e32 v163, v139, v183
	v_add_f32_e32 v165, v135, v201
	v_mul_f32_e32 v167, 0xbfb8aa3b, v167
	v_mul_f32_e32 v169, 0xbfb8aa3b, v169
	v_mul_f32_e32 v173, 0xbfb8aa3b, v173
	v_mul_f32_e32 v178, 0xbfb8aa3b, v178
	v_mul_f32_e32 v147, 0xbfb8aa3b, v147
	v_mul_f32_e32 v149, 0xbfb8aa3b, v149
	v_mul_f32_e32 v163, 0xbfb8aa3b, v163
	v_mul_f32_e32 v165, 0xbfb8aa3b, v165
	v_exp_f32_e32 v167, v167
	v_exp_f32_e32 v169, v169
	v_exp_f32_e32 v173, v173
	v_exp_f32_e32 v178, v178
	v_exp_f32_e32 v147, v147
	v_exp_f32_e32 v149, v149
	v_exp_f32_e32 v163, v163
	v_exp_f32_e32 v165, v165
	v_add_f32_e32 v167, 1.0, v167
	v_add_f32_e32 v169, 1.0, v169
	v_add_f32_e32 v173, 1.0, v173
	v_add_f32_e32 v178, 1.0, v178
	v_add_f32_e32 v147, 1.0, v147
	v_add_f32_e32 v149, 1.0, v149
	v_add_f32_e32 v163, 1.0, v163
	v_add_f32_e32 v165, 1.0, v165
	v_rcp_f32_e32 v167, v167
	v_rcp_f32_e32 v169, v169
	v_rcp_f32_e32 v173, v173
	v_rcp_f32_e32 v178, v178
	v_rcp_f32_e32 v147, v147
	v_rcp_f32_e32 v149, v149
	v_rcp_f32_e32 v163, v163
	v_rcp_f32_e32 v165, v165
	v_cvt_pk_bf16_f32 v201, v167, v173
	v_cvt_pk_bf16_f32 v203, v169, v178
	v_pk_mul_f32 v[178:179], v[32:33], v[172:173] op_sel_hi:[1,0]
	v_pk_mul_f32 v[182:183], v[30:31], v[172:173] op_sel_hi:[1,0]
	v_pk_mul_f32 v[196:197], v[28:29], v[172:173] op_sel_hi:[1,0]
	v_pk_mul_f32 v[172:173], v[26:27], v[172:173] op_sel_hi:[1,0]
	v_cvt_pk_bf16_f32 v200, v147, v163
	v_cvt_pk_bf16_f32 v202, v149, v165
	v_add_f32_e32 v147, v182, v142
	v_add_f32_e32 v149, v172, v130
	v_add_f32_e32 v163, v183, v143
	v_add_f32_e32 v165, v173, v131
	v_add_f32_e32 v167, v178, v144
	v_add_f32_e32 v169, v196, v132
	v_add_f32_e32 v172, v179, v145
	v_add_f32_e32 v173, v197, v133
	v_mul_f32_e32 v147, 0xbfb8aa3b, v147
	v_mul_f32_e32 v149, 0xbfb8aa3b, v149
	v_mul_f32_e32 v163, 0xbfb8aa3b, v163
	v_mul_f32_e32 v165, 0xbfb8aa3b, v165
	v_mul_f32_e32 v167, 0xbfb8aa3b, v167
	v_mul_f32_e32 v169, 0xbfb8aa3b, v169
	v_mul_f32_e32 v172, 0xbfb8aa3b, v172
	v_mul_f32_e32 v173, 0xbfb8aa3b, v173
	v_exp_f32_e32 v147, v147
	v_exp_f32_e32 v149, v149
	v_exp_f32_e32 v163, v163
	v_exp_f32_e32 v165, v165
	v_exp_f32_e32 v167, v167
	v_exp_f32_e32 v169, v169
	v_exp_f32_e32 v172, v172
	v_exp_f32_e32 v173, v173
	v_add_f32_e32 v147, 1.0, v147
	v_add_f32_e32 v149, 1.0, v149
	v_add_f32_e32 v163, 1.0, v163
	v_add_f32_e32 v165, 1.0, v165
	v_add_f32_e32 v167, 1.0, v167
	v_add_f32_e32 v169, 1.0, v169
	v_add_f32_e32 v172, 1.0, v172
	v_add_f32_e32 v173, 1.0, v173
	v_rcp_f32_e32 v147, v147
	v_rcp_f32_e32 v149, v149
	v_rcp_f32_e32 v163, v163
	v_rcp_f32_e32 v165, v165
	v_rcp_f32_e32 v167, v167
	v_rcp_f32_e32 v169, v169
	v_rcp_f32_e32 v172, v172
	v_rcp_f32_e32 v173, v173
	v_mad_i64_i32 v[170:171], s[0:1], v170, s33, v[174:175]
	v_lshl_add_u64 v[170:171], v[170:171], 0, v[176:177]
	global_store_dwordx4 v[170:171], v[200:203], off
	v_pk_mul_f32 v[178:179], v[84:85], v[168:169] op_sel_hi:[1,0]
	v_pk_mul_f32 v[182:183], v[82:83], v[168:169] op_sel_hi:[1,0]
	v_cvt_pk_bf16_f32 v200, v147, v163
	v_cvt_pk_bf16_f32 v201, v167, v172
	v_cvt_pk_bf16_f32 v202, v149, v165
	v_cvt_pk_bf16_f32 v203, v169, v173
	global_store_dwordx4 v[170:171], v[200:203], off offset:256
	v_pk_mul_f32 v[170:171], v[88:89], v[168:169] op_sel_hi:[1,0]
	v_pk_mul_f32 v[172:173], v[86:87], v[168:169] op_sel_hi:[1,0]
; __device__ __forceinline__ unsigned pk2(float lo, float hi) { f32x2 v = {lo, hi}; bf16x2_t b = __builtin_convertvector(v, bf16x2_t); return __builtin_bit_cast(unsigned, b); }
; __device__ __forceinline__ float sigmoidf_(float x) { return __builtin_amdgcn_rcpf(1.0f + __builtin_amdgcn_exp2f(-1.4426950408889634f * x)); }
;     __device__ __forceinline__ void gate_tile(const Acc& acc, const Unit& u, int wr, int wc, int fr, int fq) const {
;     ...
;             for (int m = 0; m < 4; ++m) { bf16_t* rowp = GT + (size_t)(row0 + ai * HALF + m * 16) * GT_LD + col0; const float rs = rsv[ai * 4 + m];
; #pragma unroll
;                 for (int bj = 0; bj < 2; ++bj) { f32x4 v0 = acc[ai][bj][m][0] * rs, v1 = acc[ai][bj][m][1] * rs;
; #pragma unroll
;                     for (int i = 0; i < 4; ++i) { v0[i] = sigmoidf_(v0[i] + bb[bj][0][i]); v1[i] = sigmoidf_(v1[i] + bb[bj][1][i]); }
;                     u32x4 w; w.x = pk2(v0[0], v0[1]); w.y = pk2(v0[2], v0[3]); w.z = pk2(v1[0], v1[1]); w.w = pk2(v1[2], v1[3]);
;                     *(u32x4*)(rowp + bj * HALF) = w; } asm volatile("" ::: "memory"); }
	v_add_f32_e32 v169, v140, v170
	v_add_f32_e32 v170, v136, v178
	v_mul_f32_e32 v170, 0xbfb8aa3b, v170
	v_exp_f32_e32 v170, v170
	v_add_f32_e32 v163, v139, v173
	v_add_f32_e32 v147, v138, v172
	v_add_f32_e32 v149, v134, v182
	v_add_f32_e32 v170, 1.0, v170
	v_rcp_f32_e32 v173, v170
	v_add_f32_e32 v170, v141, v171
	v_mul_f32_e32 v170, 0xbfb8aa3b, v170
	v_exp_f32_e32 v170, v170
	v_add_f32_e32 v165, v135, v183
	v_mul_f32_e32 v147, 0xbfb8aa3b, v147
	v_mul_f32_e32 v149, 0xbfb8aa3b, v149
	v_add_f32_e32 v170, 1.0, v170
	v_rcp_f32_e32 v171, v170
	v_add_f32_e32 v170, v137, v179
	v_mul_f32_e32 v163, 0xbfb8aa3b, v163
	v_mul_f32_e32 v165, 0xbfb8aa3b, v165
	v_mul_f32_e32 v169, 0xbfb8aa3b, v169
	v_mul_f32_e32 v170, 0xbfb8aa3b, v170
	v_exp_f32_e32 v147, v147
	v_exp_f32_e32 v149, v149
	v_exp_f32_e32 v163, v163
	v_exp_f32_e32 v165, v165
	v_exp_f32_e32 v169, v169
	v_exp_f32_e32 v170, v170
	v_add_f32_e32 v147, 1.0, v147
	v_add_f32_e32 v149, 1.0, v149
	v_add_f32_e32 v163, 1.0, v163
	v_add_f32_e32 v165, 1.0, v165
	v_add_f32_e32 v169, 1.0, v169
	v_add_f32_e32 v170, 1.0, v170
	v_rcp_f32_e32 v147, v147
	v_rcp_f32_e32 v149, v149
	v_rcp_f32_e32 v163, v163
	v_rcp_f32_e32 v165, v165
	v_rcp_f32_e32 v169, v169
	v_rcp_f32_e32 v178, v170
	v_mad_i64_i32 v[166:167], s[0:1], v166, s33, v[174:175]
	v_lshl_add_u64 v[166:167], v[166:167], 0, v[176:177]
	v_cvt_pk_bf16_f32 v170, v147, v163
	v_cvt_pk_bf16_f32 v171, v169, v171
	v_cvt_pk_bf16_f32 v172, v149, v165
	v_cvt_pk_bf16_f32 v173, v173, v178
	global_store_dwordx4 v[166:167], v[170:173], off
	v_pk_mul_f32 v[178:179], v[20:21], v[168:169] op_sel_hi:[1,0]
	s_nop 0
	v_pk_mul_f32 v[170:171], v[24:25], v[168:169] op_sel_hi:[1,0]
	v_pk_mul_f32 v[172:173], v[22:23], v[168:169] op_sel_hi:[1,0]
	v_pk_mul_f32 v[168:169], v[18:19], v[168:169] op_sel_hi:[1,0]
	v_add_f32_e32 v147, v142, v172
	v_add_f32_e32 v149, v130, v168
	v_add_f32_e32 v168, v144, v170
	v_mul_f32_e32 v168, 0xbfb8aa3b, v168
	v_exp_f32_e32 v168, v168
	v_add_f32_e32 v165, v131, v169
	v_add_f32_e32 v163, v143, v173
	v_mul_f32_e32 v147, 0xbfb8aa3b, v147
	v_add_f32_e32 v168, 1.0, v168
	v_rcp_f32_e32 v169, v168
	v_add_f32_e32 v168, v132, v178
	v_mul_f32_e32 v168, 0xbfb8aa3b, v168
	v_exp_f32_e32 v168, v168
	v_mul_f32_e32 v149, 0xbfb8aa3b, v149
	v_mul_f32_e32 v163, 0xbfb8aa3b, v163
	v_mul_f32_e32 v165, 0xbfb8aa3b, v165
	v_add_f32_e32 v168, 1.0, v168
	v_rcp_f32_e32 v172, v168
	v_add_f32_e32 v168, v145, v171
	v_mul_f32_e32 v168, 0xbfb8aa3b, v168
	v_exp_f32_e32 v168, v168
	v_exp_f32_e32 v147, v147
	v_exp_f32_e32 v149, v149
	v_exp_f32_e32 v163, v163
	v_add_f32_e32 v168, 1.0, v168
	v_rcp_f32_e32 v170, v168
	v_add_f32_e32 v168, v133, v179
	v_mul_f32_e32 v168, 0xbfb8aa3b, v168
	v_exp_f32_e32 v165, v165
	v_exp_f32_e32 v168, v168
	v_add_f32_e32 v147, 1.0, v147
	v_add_f32_e32 v149, 1.0, v149
	v_add_f32_e32 v163, 1.0, v163
	v_add_f32_e32 v165, 1.0, v165
	v_add_f32_e32 v168, 1.0, v168
	v_rcp_f32_e32 v147, v147
	v_rcp_f32_e32 v149, v149
	v_rcp_f32_e32 v163, v163
	v_rcp_f32_e32 v165, v165
	v_rcp_f32_e32 v171, v168
	v_cvt_pk_bf16_f32 v169, v169, v170
	v_cvt_pk_bf16_f32 v168, v147, v163
	v_cvt_pk_bf16_f32 v170, v149, v165
	v_cvt_pk_bf16_f32 v171, v172, v171
	global_store_dwordx4 v[166:167], v[168:171], off offset:256
	v_pk_mul_f32 v[166:167], v[80:81], v[164:165] op_sel_hi:[1,0]
	v_pk_mul_f32 v[172:173], v[74:75], v[164:165] op_sel_hi:[1,0]
	v_add_f32_e32 v166, v140, v166
	v_mul_f32_e32 v166, 0xbfb8aa3b, v166
	v_exp_f32_e32 v166, v166
	v_pk_mul_f32 v[168:169], v[78:79], v[164:165] op_sel_hi:[1,0]
	v_pk_mul_f32 v[170:171], v[76:77], v[164:165] op_sel_hi:[1,0]
	v_add_f32_e32 v165, v139, v169
	v_add_f32_e32 v166, 1.0, v166
	v_rcp_f32_e32 v169, v166
	v_add_f32_e32 v166, v136, v170
	v_mul_f32_e32 v166, 0xbfb8aa3b, v166
	v_exp_f32_e32 v166, v166
	v_add_f32_e32 v147, v138, v168
	v_add_f32_e32 v149, v134, v172
	v_add_f32_e32 v168, v135, v173
	v_add_f32_e32 v166, 1.0, v166
	v_rcp_f32_e32 v170, v166
	v_add_f32_e32 v166, v141, v167
	v_mul_f32_e32 v166, 0xbfb8aa3b, v166
	v_exp_f32_e32 v166, v166
	v_mul_f32_e32 v147, 0xbfb8aa3b, v147
	v_mul_f32_e32 v149, 0xbfb8aa3b, v149
	v_mul_f32_e32 v165, 0xbfb8aa3b, v165
	v_add_f32_e32 v166, 1.0, v166
	v_rcp_f32_e32 v167, v166
	v_add_f32_e32 v166, v137, v171
	v_mul_f32_e32 v168, 0xbfb8aa3b, v168
	v_mul_f32_e32 v166, 0xbfb8aa3b, v166
	v_exp_f32_e32 v147, v147
	v_exp_f32_e32 v149, v149
	v_exp_f32_e32 v165, v165
	v_exp_f32_e32 v168, v168
	v_exp_f32_e32 v166, v166
	v_add_f32_e32 v147, 1.0, v147
	v_add_f32_e32 v149, 1.0, v149
	v_add_f32_e32 v165, 1.0, v165
	v_add_f32_e32 v168, 1.0, v168
	v_add_f32_e32 v166, 1.0, v166
	v_rcp_f32_e32 v147, v147
	v_rcp_f32_e32 v149, v149
	v_rcp_f32_e32 v165, v165
	v_rcp_f32_e32 v168, v168
	v_rcp_f32_e32 v171, v166
	v_mad_i64_i32 v[162:163], s[0:1], v162, s33, v[174:175]
	v_lshl_add_u64 v[162:163], v[162:163], 0, v[176:177]
	v_cvt_pk_bf16_f32 v166, v147, v165
	v_cvt_pk_bf16_f32 v167, v169, v167
	v_cvt_pk_bf16_f32 v168, v149, v168
	v_cvt_pk_bf16_f32 v169, v170, v171
	global_store_dwordx4 v[162:163], v[166:169], off
	v_pk_mul_f32 v[170:171], v[12:13], v[164:165] op_sel_hi:[1,0]
	s_nop 0
; __device__ __forceinline__ unsigned pk2(float lo, float hi) { f32x2 v = {lo, hi}; bf16x2_t b = __builtin_convertvector(v, bf16x2_t); return __builtin_bit_cast(unsigned, b); }
; __device__ __forceinline__ float sigmoidf_(float x) { return __builtin_amdgcn_rcpf(1.0f + __builtin_amdgcn_exp2f(-1.4426950408889634f * x)); }
;     __device__ __forceinline__ void gate_tile(const Acc& acc, const Unit& u, int wr, int wc, int fr, int fq) const {
;     ...
;             for (int m = 0; m < 4; ++m) { bf16_t* rowp = GT + (size_t)(row0 + ai * HALF + m * 16) * GT_LD + col0; const float rs = rsv[ai * 4 + m];
; #pragma unroll
;                 for (int bj = 0; bj < 2; ++bj) { f32x4 v0 = acc[ai][bj][m][0] * rs, v1 = acc[ai][bj][m][1] * rs;
; #pragma unroll
;                     for (int i = 0; i < 4; ++i) { v0[i] = sigmoidf_(v0[i] + bb[bj][0][i]); v1[i] = sigmoidf_(v1[i] + bb[bj][1][i]); }
;                     u32x4 w; w.x = pk2(v0[0], v0[1]); w.y = pk2(v0[2], v0[3]); w.z = pk2(v1[0], v1[1]); w.w = pk2(v1[2], v1[3]);
;                     *(u32x4*)(rowp + bj * HALF) = w; } asm volatile("" ::: "memory"); }
	v_pk_mul_f32 v[166:167], v[16:17], v[164:165] op_sel_hi:[1,0]
	v_pk_mul_f32 v[168:169], v[14:15], v[164:165] op_sel_hi:[1,0]
	v_pk_mul_f32 v[164:165], v[10:11], v[164:165] op_sel_hi:[1,0]
	v_add_f32_e32 v147, v142, v168
	v_add_f32_e32 v165, v131, v165
	v_mul_f32_e32 v165, 0xbfb8aa3b, v165
	v_exp_f32_e32 v165, v165
	v_add_f32_e32 v149, v130, v164
	v_add_f32_e32 v164, v143, v169
	v_mul_f32_e32 v147, 0xbfb8aa3b, v147
	v_add_f32_e32 v165, 1.0, v165
	v_rcp_f32_e32 v168, v165
	v_add_f32_e32 v165, v144, v166
	v_add_f32_e32 v166, v132, v170
	v_mul_f32_e32 v166, 0xbfb8aa3b, v166
	v_exp_f32_e32 v166, v166
	v_mul_f32_e32 v149, 0xbfb8aa3b, v149
	v_mul_f32_e32 v164, 0xbfb8aa3b, v164
	v_mul_f32_e32 v165, 0xbfb8aa3b, v165
	v_add_f32_e32 v166, 1.0, v166
	v_rcp_f32_e32 v169, v166
	v_add_f32_e32 v166, v145, v167
	v_add_f32_e32 v167, v133, v171
	v_mul_f32_e32 v166, 0xbfb8aa3b, v166
	v_mul_f32_e32 v167, 0xbfb8aa3b, v167
	v_exp_f32_e32 v147, v147
	v_exp_f32_e32 v149, v149
	v_exp_f32_e32 v164, v164
	v_exp_f32_e32 v165, v165
	v_exp_f32_e32 v166, v166
	v_exp_f32_e32 v167, v167
	v_add_f32_e32 v147, 1.0, v147
	v_add_f32_e32 v149, 1.0, v149
	v_add_f32_e32 v164, 1.0, v164
	v_add_f32_e32 v165, 1.0, v165
	v_add_f32_e32 v166, 1.0, v166
	v_add_f32_e32 v167, 1.0, v167
	v_rcp_f32_e32 v147, v147
	v_rcp_f32_e32 v149, v149
	v_rcp_f32_e32 v164, v164
	v_rcp_f32_e32 v165, v165
	v_rcp_f32_e32 v166, v166
	v_rcp_f32_e32 v167, v167
	v_cvt_pk_bf16_f32 v164, v147, v164
	v_cvt_pk_bf16_f32 v165, v165, v166
	v_cvt_pk_bf16_f32 v166, v149, v168
	v_cvt_pk_bf16_f32 v167, v169, v167
	global_store_dwordx4 v[162:163], v[164:167], off offset:256
	v_pk_mul_f32 v[168:169], v[66:67], v[160:161] op_sel_hi:[1,0]
	v_pk_mul_f32 v[162:163], v[72:73], v[160:161] op_sel_hi:[1,0]
	v_pk_mul_f32 v[166:167], v[68:69], v[160:161] op_sel_hi:[1,0]
	v_add_f32_e32 v134, v134, v168
	v_add_f32_e32 v135, v135, v169
	v_add_f32_e32 v136, v136, v166
	v_mul_f32_e32 v134, 0xbfb8aa3b, v134
	v_mul_f32_e32 v135, 0xbfb8aa3b, v135
	v_mul_f32_e32 v136, 0xbfb8aa3b, v136
	v_exp_f32_e32 v134, v134
	v_exp_f32_e32 v135, v135
	v_exp_f32_e32 v136, v136
	v_pk_mul_f32 v[164:165], v[70:71], v[160:161] op_sel_hi:[1,0]
	v_add_f32_e32 v134, 1.0, v134
	v_add_f32_e32 v135, 1.0, v135
	v_add_f32_e32 v136, 1.0, v136
	v_add_f32_e32 v138, v138, v164
	v_rcp_f32_e32 v147, v134
	v_add_f32_e32 v134, v139, v165
	v_rcp_f32_e32 v139, v135
	v_add_f32_e32 v135, v140, v162
	v_rcp_f32_e32 v140, v136
	v_add_f32_e32 v136, v141, v163
	v_add_f32_e32 v137, v137, v167
	v_mul_f32_e32 v138, 0xbfb8aa3b, v138
	v_mul_f32_e32 v134, 0xbfb8aa3b, v134
	v_mul_f32_e32 v135, 0xbfb8aa3b, v135
	v_mul_f32_e32 v136, 0xbfb8aa3b, v136
	v_mul_f32_e32 v137, 0xbfb8aa3b, v137
	v_exp_f32_e32 v138, v138
	v_exp_f32_e32 v134, v134
	v_exp_f32_e32 v135, v135
	v_exp_f32_e32 v136, v136
	v_exp_f32_e32 v137, v137
	v_add_f32_e32 v138, 1.0, v138
	v_add_f32_e32 v134, 1.0, v134
	v_add_f32_e32 v135, 1.0, v135
	v_add_f32_e32 v136, 1.0, v136
	v_add_f32_e32 v137, 1.0, v137
	v_rcp_f32_e32 v138, v138
	v_rcp_f32_e32 v134, v134
	v_rcp_f32_e32 v135, v135
	v_rcp_f32_e32 v136, v136
	v_rcp_f32_e32 v137, v137
	v_cvt_pk_bf16_f32 v134, v138, v134
	v_mad_i64_i32 v[148:149], s[0:1], v148, s33, v[174:175]
	v_cvt_pk_bf16_f32 v135, v135, v136
	v_cvt_pk_bf16_f32 v136, v147, v139
	v_cvt_pk_bf16_f32 v137, v140, v137
	v_pk_mul_f32 v[138:139], v[4:5], v[160:161] op_sel_hi:[1,0]
	v_pk_mul_f32 v[140:141], v[2:3], v[160:161] op_sel_hi:[1,0]
	v_add_f32_e32 v132, v132, v138
	v_add_f32_e32 v130, v130, v140
	v_add_f32_e32 v131, v131, v141
	v_mul_f32_e32 v130, 0xbfb8aa3b, v130
	v_mul_f32_e32 v131, 0xbfb8aa3b, v131
	v_mul_f32_e32 v132, 0xbfb8aa3b, v132
	v_exp_f32_e32 v130, v130
	v_exp_f32_e32 v131, v131
	v_exp_f32_e32 v132, v132
	v_lshl_add_u64 v[148:149], v[148:149], 0, v[176:177]
	global_store_dwordx4 v[148:149], v[134:137], off
	v_add_f32_e32 v130, 1.0, v130
	v_add_f32_e32 v131, 1.0, v131
	v_pk_mul_f32 v[134:135], v[8:9], v[160:161] op_sel_hi:[1,0]
	v_pk_mul_f32 v[136:137], v[6:7], v[160:161] op_sel_hi:[1,0]
	v_add_f32_e32 v132, 1.0, v132
	v_add_f32_e32 v136, v142, v136
	v_rcp_f32_e32 v140, v130
	v_add_f32_e32 v130, v143, v137
	v_rcp_f32_e32 v137, v131
	v_add_f32_e32 v131, v144, v134
	v_rcp_f32_e32 v134, v132
	v_add_f32_e32 v132, v145, v135
	v_add_f32_e32 v133, v133, v139
	v_mul_f32_e32 v136, 0xbfb8aa3b, v136
	v_mul_f32_e32 v130, 0xbfb8aa3b, v130
	v_mul_f32_e32 v131, 0xbfb8aa3b, v131
	v_mul_f32_e32 v132, 0xbfb8aa3b, v132
	v_mul_f32_e32 v133, 0xbfb8aa3b, v133
	v_exp_f32_e32 v136, v136
	v_exp_f32_e32 v130, v130
	v_exp_f32_e32 v131, v131
	v_exp_f32_e32 v132, v132
	v_exp_f32_e32 v133, v133
	v_add_f32_e32 v136, 1.0, v136
	v_add_f32_e32 v130, 1.0, v130
	v_add_f32_e32 v131, 1.0, v131
	v_add_f32_e32 v132, 1.0, v132
	v_add_f32_e32 v133, 1.0, v133
	v_rcp_f32_e32 v136, v136
	v_rcp_f32_e32 v130, v130
	v_rcp_f32_e32 v131, v131
	v_rcp_f32_e32 v132, v132
	v_rcp_f32_e32 v133, v133
	v_cvt_pk_bf16_f32 v130, v136, v130
	v_cvt_pk_bf16_f32 v131, v131, v132
	v_cvt_pk_bf16_f32 v132, v140, v137
	v_cvt_pk_bf16_f32 v133, v134, v133
	global_store_dwordx4 v[148:149], v[130:133], off offset:256
	s_cbranch_execz .LBB0_298

; __device__ __forceinline__ float wave_sum(float v) {
; #pragma unroll
;     for (int o = 1; o < 64; o <<= 1) v += __shfl_xor(v, o);
;     return v;
; __device__ __forceinline__ void final_norm_phase(float* X, const float* __restrict__ g, int gw, int NGW, int lane) {
;     ...
;     for (int row = gw; row < TOK; row += NGW) {
;         f32x4* xr = (f32x4*)(X + (size_t)row * DM) + lane;
;         f32x4 v[4]; float ss = 0.f;
; #pragma unroll
;         for (int j = 0; j < 4; ++j) { v[j] = xr[64 * j]; ss += (v[j].x * v[j].x + v[j].y * v[j].y) + (v[j].z * v[j].z + v[j].w * v[j].w); }
;         ss = wave_sum(ss);
;         const float rinv = 1.0f / sqrtf(ss * (1.0f / DM) + EPS);
; #pragma unroll
;         for (int j = 0; j < 4; ++j) xr[64 * j] = v[j] * rinv * gv[j];
;     }
.LBB0_802:
	global_load_dwordx4 v[26:29], v[18:19], off
	global_load_dwordx4 v[30:33], v[18:19], off offset:1024
	s_waitcnt vmcnt(0)
	global_load_dwordx4 v[34:37], v[18:19], off offset:3072
	global_load_dwordx4 v[38:41], v[18:19], off offset:2048
	s_add_i32 s2, s2, s94
	s_cmpk_gt_i32 s2, 0x7fff
	s_waitcnt lgkmcnt(0)
	v_pk_mul_f32 v[42:43], v[28:29], v[28:29]
	v_pk_mul_f32 v[44:45], v[26:27], v[26:27]
	v_pk_mul_f32 v[46:47], v[32:33], v[32:33]
	v_pk_mul_f32 v[48:49], v[30:31], v[30:31]
	v_pk_mov_b32 v[52:53], v[44:45], v[42:43] op_sel:[1,0]
	v_mov_b32_e32 v45, v43
	v_pk_mov_b32 v[42:43], v[48:49], v[46:47] op_sel:[1,0]
	v_mov_b32_e32 v49, v47
	s_waitcnt vmcnt(0)
	v_mul_f32_e32 v0, v39, v39
	v_mul_f32_e32 v50, v41, v41
	v_pk_add_f32 v[44:45], v[52:53], v[44:45]
	v_pk_add_f32 v[42:43], v[42:43], v[48:49]
	v_mul_f32_e32 v54, v34, v34
	v_mul_f32_e32 v55, v35, v35
	v_mul_f32_e32 v56, v36, v36
	v_mul_f32_e32 v57, v37, v37
	v_pk_fma_f32 v[46:47], v[38:39], v[38:39], v[0:1] op_sel_hi:[1,1,0]
	v_pk_fma_f32 v[50:51], v[40:41], v[40:41], v[50:51] op_sel_hi:[1,1,0]
	v_pk_add_f32 v[44:45], v[44:45], v[44:45] op_sel:[0,1] op_sel_hi:[1,0]
	v_pk_add_f32 v[42:43], v[42:43], v[42:43] op_sel:[0,1] op_sel_hi:[1,0]
	v_mov_b32_e32 v47, v56
	v_mov_b32_e32 v51, v57
	v_mov_b32_e32 v45, v54
	v_mov_b32_e32 v43, v55
	v_pk_add_f32 v[46:47], v[46:47], v[50:51]
	v_pk_add_f32 v[42:43], v[44:45], v[42:43]
	s_nop 0
	v_pk_add_f32 v[42:43], v[42:43], v[46:47]
	s_nop 0
	v_add_f32_e32 v0, v42, v43
	ds_bpermute_b32 v42, v20, v0
	s_waitcnt lgkmcnt(0)
	v_add_f32_e32 v0, v0, v42
	ds_bpermute_b32 v42, v21, v0
	s_waitcnt lgkmcnt(0)
	v_add_f32_e32 v0, v0, v42
	ds_bpermute_b32 v42, v22, v0
	s_waitcnt lgkmcnt(0)
	v_add_f32_e32 v0, v0, v42
	ds_bpermute_b32 v42, v23, v0
	s_waitcnt lgkmcnt(0)
	v_add_f32_e32 v0, v0, v42
	ds_bpermute_b32 v42, v24, v0
	s_waitcnt lgkmcnt(0)
	v_add_f32_e32 v0, v0, v42
	v_mov_b32_e32 v42, v0
	s_nop 1
	v_permlane32_swap_b32_e32 v42, v0
	s_waitcnt lgkmcnt(0)
	v_add_f32_e32 v0, v0, v42
	v_fmamk_f32 v0, v0, 0x3a800000, v225
	v_mul_f32_e32 v42, 0x4f800000, v0
	v_cmp_gt_f32_e32 vcc, s3, v0
	s_nop 1
	v_cndmask_b32_e32 v0, v0, v42, vcc
	v_sqrt_f32_e32 v42, v0
	s_nop 0
	v_add_u32_e32 v43, -1, v42
	v_add_u32_e32 v44, 1, v42
	v_fma_f32 v45, -v43, v42, v0
	v_fma_f32 v46, -v44, v42, v0
	v_cmp_ge_f32_e64 s[38:39], 0, v45
	s_nop 1
	v_cndmask_b32_e64 v42, v42, v43, s[38:39]
	v_cmp_lt_f32_e64 s[38:39], 0, v46
	s_nop 1
	v_cndmask_b32_e64 v42, v42, v44, s[38:39]
	v_mul_f32_e32 v43, 0x37800000, v42
	v_cndmask_b32_e32 v42, v42, v43, vcc
	v_cmp_class_f32_e32 vcc, v0, v226
	s_nop 1
	v_cndmask_b32_e32 v0, v42, v0, vcc
	v_div_scale_f32 v42, s[12:13], v0, v0, 1.0
	v_rcp_f32_e32 v43, v42
	v_div_scale_f32 v44, vcc, 1.0, v0, 1.0
	v_fma_f32 v45, -v42, v43, 1.0
	v_fmac_f32_e32 v43, v45, v43
	v_mul_f32_e32 v45, v44, v43
	v_fma_f32 v46, -v42, v45, v44
	v_fmac_f32_e32 v45, v46, v43
	v_fma_f32 v42, -v42, v45, v44
	v_div_fmas_f32 v42, v42, v43, v45
	v_div_fixup_f32 v0, v42, v0, 1.0
	v_pk_mul_f32 v[26:27], v[26:27], v[0:1] op_sel_hi:[1,0]
	v_pk_mul_f32 v[28:29], v[28:29], v[0:1] op_sel_hi:[1,0]
	v_pk_mul_f32 v[30:31], v[30:31], v[0:1] op_sel_hi:[1,0]
	v_pk_mul_f32 v[32:33], v[32:33], v[0:1] op_sel_hi:[1,0]
	v_pk_mul_f32 v[38:39], v[38:39], v[0:1] op_sel_hi:[1,0]
	v_pk_mul_f32 v[40:41], v[40:41], v[0:1] op_sel_hi:[1,0]
	v_pk_mul_f32 v[42:43], v[34:35], v[0:1] op_sel_hi:[1,0]
	v_pk_mul_f32 v[44:45], v[36:37], v[0:1] op_sel_hi:[1,0]
	v_pk_mul_f32 v[28:29], v[4:5], v[28:29]
	v_pk_mul_f32 v[26:27], v[2:3], v[26:27]
	v_pk_mul_f32 v[32:33], v[8:9], v[32:33]
	v_pk_mul_f32 v[30:31], v[6:7], v[30:31]
	v_pk_mul_f32 v[36:37], v[12:13], v[40:41]
	v_pk_mul_f32 v[34:35], v[10:11], v[38:39]
	v_pk_mul_f32 v[40:41], v[16:17], v[44:45]
	v_pk_mul_f32 v[38:39], v[14:15], v[42:43]
	global_store_dwordx4 v[18:19], v[26:29], off
	global_store_dwordx4 v[18:19], v[30:33], off offset:1024
	global_store_dwordx4 v[18:19], v[34:37], off offset:2048
	global_store_dwordx4 v[18:19], v[38:41], off offset:3072
	v_lshl_add_u64 v[18:19], v[18:19], 0, s[0:1]
	s_cbranch_scc0 .LBB0_802
	s_getpc_b64 s[98:99]
